# speedup vs baseline: 1.1435x; 1.0037x over previous
.LBB0_220:
	s_add_i32 s12, s11, 0xffff8000
	s_and_b32 s12, s12, 0x8000
	s_lshl_b32 s12, s12, 1
	v_lshl_or_b32 v235, v14, 1, s12
	v_add_u32_e32 v234, v235, v10
	v_add_u32_e32 v235, v235, v8
	ds_read_b128 v[16:19], v234
	ds_read_b128 v[20:23], v235 offset:32768
	ds_read_b128 v[24:27], v235 offset:36864
	ds_read_b128 v[28:31], v235 offset:40960
	ds_read_b128 v[32:35], v235 offset:45056
	ds_read_b128 v[148:151], v234 offset:4096
	s_waitcnt lgkmcnt(4)
	v_mfma_f32_32x32x16_bf16 a[224:239], v[16:19], v[20:23], a[224:239]
	s_waitcnt lgkmcnt(3)
	v_mfma_f32_32x32x16_bf16 a[160:175], v[16:19], v[24:27], a[160:175]
	s_and_b32 s98, s11, 0x8000
	s_lshl_b32 s98, s98, 1
	s_add_i32 s98, s62, s98
	v_lshl_add_u64 v[100:101], v[0:1], 0, s[4:5]
	v_lshl_add_u64 v[104:105], v[100:101], 0, s[16:17]
	s_mov_b32 m0, s98
	s_add_i32 s99, s98, 0x8000
	global_load_lds_dwordx4 v[104:105], off
	s_waitcnt lgkmcnt(2)
	v_mfma_f32_32x32x16_bf16 a[96:111], v[16:19], v[28:31], a[96:111]
	v_lshl_add_u64 v[104:105], v[4:5], 0, s[4:5]
	v_lshl_add_u64 v[114:115], v[104:105], 0, s[38:39]
	s_mov_b32 m0, s99
	s_nop 0
	global_load_lds_dwordx4 v[114:115], off
	s_waitcnt lgkmcnt(1)
	v_mfma_f32_32x32x16_bf16 a[32:47], v[16:19], v[32:35], a[32:47]
	v_lshl_add_u64 v[114:115], v[2:3], 0, s[4:5]
	v_lshl_add_u64 v[118:119], v[114:115], 0, s[30:31]
	s_add_i32 m0, s98, 0x400
	s_nop 0
	global_load_lds_dwordx4 v[118:119], off
	ds_read_b128 v[16:19], v234 offset:16384
	s_waitcnt lgkmcnt(1)
	v_mfma_f32_32x32x16_bf16 a[192:207], v[148:151], v[20:23], a[192:207]
	v_lshl_add_u64 v[118:119], v[6:7], 0, s[4:5]
	v_lshl_add_u64 v[144:145], v[118:119], 0, s[44:45]
	s_add_i32 m0, s98, 0x8400
	s_nop 0
	global_load_lds_dwordx4 v[144:145], off
	v_mfma_f32_32x32x16_bf16 a[128:143], v[148:151], v[24:27], a[128:143]
	v_lshl_add_u64 v[144:145], v[100:101], 0, s[68:69]
	s_add_i32 m0, s98, 0x800
	s_nop 0
	global_load_lds_dwordx4 v[144:145], off
	v_mfma_f32_32x32x16_bf16 a[64:79], v[148:151], v[28:31], a[64:79]
	v_lshl_add_u64 v[144:145], v[104:105], 0, s[2:3]
	s_add_i32 m0, s98, 0x8800
	s_nop 0
	global_load_lds_dwordx4 v[144:145], off
	v_mfma_f32_32x32x16_bf16 a[0:15], v[148:151], v[32:35], a[0:15]
	v_lshl_add_u64 v[144:145], v[114:115], 0, s[70:71]
	s_add_i32 m0, s98, 0xc00
	s_nop 0
	global_load_lds_dwordx4 v[144:145], off
	ds_read_b128 v[148:151], v234 offset:20480
	s_waitcnt lgkmcnt(1)
	v_mfma_f32_32x32x16_bf16 a[240:255], v[16:19], v[20:23], a[240:255]
	v_lshl_add_u64 v[144:145], v[118:119], 0, s[46:47]
	s_add_i32 m0, s98, 0x8c00
	s_nop 0
	global_load_lds_dwordx4 v[144:145], off
	v_mfma_f32_32x32x16_bf16 a[176:191], v[16:19], v[24:27], a[176:191]
	v_lshl_add_u64 v[144:145], v[100:101], 0, s[76:77]
	s_add_i32 m0, s98, 0x1000
	v_lshl_add_u64 v[100:101], v[100:101], 0, s[80:81]
	global_load_lds_dwordx4 v[144:145], off
	v_mfma_f32_32x32x16_bf16 a[112:127], v[16:19], v[28:31], a[112:127]
	v_lshl_add_u64 v[144:145], v[104:105], 0, s[50:51]
	s_add_i32 m0, s98, 0x9000
	s_nop 0
	global_load_lds_dwordx4 v[144:145], off
	v_mfma_f32_32x32x16_bf16 a[48:63], v[16:19], v[32:35], a[48:63]
	v_lshl_add_u64 v[144:145], v[114:115], 0, s[78:79]
	s_add_i32 m0, s98, 0x1400
	s_nop 0
	global_load_lds_dwordx4 v[144:145], off
	v_lshl_or_b32 v235, v13, 1, s12
	v_add_u32_e32 v234, v235, v10
	v_add_u32_e32 v235, v235, v8
	ds_read_b128 v[16:19], v234
	s_waitcnt lgkmcnt(1)
	v_mfma_f32_32x32x16_bf16 a[208:223], v[148:151], v[20:23], a[208:223]
	v_lshl_add_u64 v[144:145], v[118:119], 0, s[52:53]
	s_add_i32 m0, s98, 0x9400
	s_nop 0
	global_load_lds_dwordx4 v[144:145], off
	ds_read_b128 v[20:23], v235 offset:32768
	v_mfma_f32_32x32x16_bf16 a[144:159], v[148:151], v[24:27], a[144:159]
	s_add_i32 m0, s98, 0x1800
	s_nop 0
	global_load_lds_dwordx4 v[100:101], off
	ds_read_b128 v[24:27], v235 offset:36864
	v_mfma_f32_32x32x16_bf16 a[80:95], v[148:151], v[28:31], a[80:95]
	v_lshl_add_u64 v[100:101], v[104:105], 0, s[54:55]
	s_add_i32 m0, s98, 0x9800
	s_nop 0
	global_load_lds_dwordx4 v[100:101], off
	ds_read_b128 v[28:31], v235 offset:40960
	v_mfma_f32_32x32x16_bf16 a[16:31], v[148:151], v[32:35], a[16:31]
	v_lshl_add_u64 v[100:101], v[114:115], 0, s[82:83]
	s_add_i32 m0, s98, 0x1c00
	s_nop 0
	global_load_lds_dwordx4 v[100:101], off
	ds_read_b128 v[32:35], v235 offset:45056
	ds_read_b128 v[148:151], v234 offset:4096
	s_waitcnt lgkmcnt(4)
	v_mfma_f32_32x32x16_bf16 a[224:239], v[16:19], v[20:23], a[224:239]
	v_lshl_add_u64 v[100:101], v[118:119], 0, s[56:57]
	s_add_i32 m0, s98, 0x9c00
	s_nop 0
	global_load_lds_dwordx4 v[100:101], off
	s_waitcnt lgkmcnt(3)
	v_mfma_f32_32x32x16_bf16 a[160:175], v[16:19], v[24:27], a[160:175]
	s_waitcnt lgkmcnt(2)
	v_mfma_f32_32x32x16_bf16 a[96:111], v[16:19], v[28:31], a[96:111]
	s_waitcnt lgkmcnt(1)
	v_mfma_f32_32x32x16_bf16 a[32:47], v[16:19], v[32:35], a[32:47]
	ds_read_b128 v[16:19], v234 offset:16384
	s_waitcnt lgkmcnt(1)
	v_mfma_f32_32x32x16_bf16 a[192:207], v[148:151], v[20:23], a[192:207]
	v_mfma_f32_32x32x16_bf16 a[128:143], v[148:151], v[24:27], a[128:143]
	v_mfma_f32_32x32x16_bf16 a[64:79], v[148:151], v[28:31], a[64:79]
	v_mfma_f32_32x32x16_bf16 a[0:15], v[148:151], v[32:35], a[0:15]
	ds_read_b128 v[148:151], v234 offset:20480
	s_waitcnt lgkmcnt(1)
	v_mfma_f32_32x32x16_bf16 a[240:255], v[16:19], v[20:23], a[240:255]
	v_mfma_f32_32x32x16_bf16 a[176:191], v[16:19], v[24:27], a[176:191]
	v_mfma_f32_32x32x16_bf16 a[112:127], v[16:19], v[28:31], a[112:127]
	v_mfma_f32_32x32x16_bf16 a[48:63], v[16:19], v[32:35], a[48:63]
	v_lshl_or_b32 v235, v12, 1, s12
	v_add_u32_e32 v234, v235, v10
	v_add_u32_e32 v235, v235, v8
	ds_read_b128 v[16:19], v234
	s_waitcnt lgkmcnt(1)
	v_mfma_f32_32x32x16_bf16 a[208:223], v[148:151], v[20:23], a[208:223]
	ds_read_b128 v[20:23], v235 offset:32768
	v_mfma_f32_32x32x16_bf16 a[144:159], v[148:151], v[24:27], a[144:159]
	ds_read_b128 v[24:27], v235 offset:36864
	v_mfma_f32_32x32x16_bf16 a[80:95], v[148:151], v[28:31], a[80:95]
	ds_read_b128 v[28:31], v235 offset:40960
	v_mfma_f32_32x32x16_bf16 a[16:31], v[148:151], v[32:35], a[16:31]
	ds_read_b128 v[32:35], v235 offset:45056
	ds_read_b128 v[148:151], v234 offset:4096
	s_waitcnt lgkmcnt(4)
	v_mfma_f32_32x32x16_bf16 a[224:239], v[16:19], v[20:23], a[224:239]
	s_waitcnt lgkmcnt(3)
	v_mfma_f32_32x32x16_bf16 a[160:175], v[16:19], v[24:27], a[160:175]
	s_waitcnt lgkmcnt(2)
	v_mfma_f32_32x32x16_bf16 a[96:111], v[16:19], v[28:31], a[96:111]
	s_waitcnt lgkmcnt(1)
	v_mfma_f32_32x32x16_bf16 a[32:47], v[16:19], v[32:35], a[32:47]
	ds_read_b128 v[16:19], v234 offset:16384
	s_waitcnt lgkmcnt(1)
	v_mfma_f32_32x32x16_bf16 a[192:207], v[148:151], v[20:23], a[192:207]
	v_mfma_f32_32x32x16_bf16 a[128:143], v[148:151], v[24:27], a[128:143]
	v_mfma_f32_32x32x16_bf16 a[64:79], v[148:151], v[28:31], a[64:79]
	v_mfma_f32_32x32x16_bf16 a[0:15], v[148:151], v[32:35], a[0:15]
	ds_read_b128 v[148:151], v234 offset:20480
	s_waitcnt lgkmcnt(1)
	v_mfma_f32_32x32x16_bf16 a[240:255], v[16:19], v[20:23], a[240:255]
	v_mfma_f32_32x32x16_bf16 a[176:191], v[16:19], v[24:27], a[176:191]
	v_mfma_f32_32x32x16_bf16 a[112:127], v[16:19], v[28:31], a[112:127]
	v_mfma_f32_32x32x16_bf16 a[48:63], v[16:19], v[32:35], a[48:63]
	v_lshl_or_b32 v235, v11, 1, s12
	v_add_u32_e32 v234, v235, v10
	v_add_u32_e32 v235, v235, v8
	ds_read_b128 v[16:19], v234
	s_waitcnt lgkmcnt(1)
	v_mfma_f32_32x32x16_bf16 a[208:223], v[148:151], v[20:23], a[208:223]
	ds_read_b128 v[20:23], v235 offset:32768
	v_mfma_f32_32x32x16_bf16 a[144:159], v[148:151], v[24:27], a[144:159]
	ds_read_b128 v[24:27], v235 offset:36864
	v_mfma_f32_32x32x16_bf16 a[80:95], v[148:151], v[28:31], a[80:95]
	ds_read_b128 v[28:31], v235 offset:40960
	v_mfma_f32_32x32x16_bf16 a[16:31], v[148:151], v[32:35], a[16:31]
	ds_read_b128 v[32:35], v235 offset:45056
	ds_read_b128 v[148:151], v234 offset:4096
	s_waitcnt lgkmcnt(4)
	v_mfma_f32_32x32x16_bf16 a[224:239], v[16:19], v[20:23], a[224:239]
	s_waitcnt lgkmcnt(3)
	v_mfma_f32_32x32x16_bf16 a[160:175], v[16:19], v[24:27], a[160:175]
	s_waitcnt lgkmcnt(2)
	v_mfma_f32_32x32x16_bf16 a[96:111], v[16:19], v[28:31], a[96:111]
	s_waitcnt lgkmcnt(1)
	v_mfma_f32_32x32x16_bf16 a[32:47], v[16:19], v[32:35], a[32:47]
	ds_read_b128 v[16:19], v234 offset:16384
	s_waitcnt lgkmcnt(1)
	v_mfma_f32_32x32x16_bf16 a[192:207], v[148:151], v[20:23], a[192:207]
	v_mfma_f32_32x32x16_bf16 a[128:143], v[148:151], v[24:27], a[128:143]
	v_mfma_f32_32x32x16_bf16 a[64:79], v[148:151], v[28:31], a[64:79]
	v_mfma_f32_32x32x16_bf16 a[0:15], v[148:151], v[32:35], a[0:15]
	ds_read_b128 v[148:151], v234 offset:20480
	s_waitcnt lgkmcnt(1)
	v_mfma_f32_32x32x16_bf16 a[240:255], v[16:19], v[20:23], a[240:255]
	v_mfma_f32_32x32x16_bf16 a[176:191], v[16:19], v[24:27], a[176:191]
	v_mfma_f32_32x32x16_bf16 a[112:127], v[16:19], v[28:31], a[112:127]
	v_mfma_f32_32x32x16_bf16 a[48:63], v[16:19], v[32:35], a[48:63]
	s_waitcnt vmcnt(0)
	s_waitcnt vmcnt(0) lgkmcnt(0)
	s_barrier
	s_add_u32 s4, s4, 0x80
	s_addc_u32 s5, s5, 0
	s_add_i32 s11, s11, 0x8000
	s_cmpk_lg_i32 s4, 0x780
	v_mfma_f32_32x32x16_bf16 a[208:223], v[148:151], v[20:23], a[208:223]
	v_mfma_f32_32x32x16_bf16 a[144:159], v[148:151], v[24:27], a[144:159]
	v_mfma_f32_32x32x16_bf16 a[80:95], v[148:151], v[28:31], a[80:95]
	v_mfma_f32_32x32x16_bf16 a[16:31], v[148:151], v[32:35], a[16:31]
	s_cbranch_scc1 .LBB0_220
	v_lshlrev_b32_e32 v4, 1, v14
	s_mov_b32 s4, 0x10000
	v_add3_u32 v9, v10, v4, s4
	ds_read_b128 v[0:3], v9
	ds_read_b128 v[36:39], v9 offset:20480
	s_mov_b32 s5, 0x18000
	v_add3_u32 v22, v8, v4, s5
	ds_read_b128 v[4:7], v22
	ds_read_b128 v[14:17], v22 offset:4096
	ds_read_b128 v[18:21], v22 offset:8192
	ds_read_b128 v[124:127], v22 offset:12288
	s_waitcnt lgkmcnt(3)
	v_mfma_f32_32x32x16_bf16 a[224:239], v[0:3], v[4:7], a[224:239]
	v_lshlrev_b32_e32 v11, 1, v11
	s_waitcnt lgkmcnt(2)
	v_mfma_f32_32x32x16_bf16 a[160:175], v[0:3], v[14:17], a[160:175]
	s_waitcnt lgkmcnt(1)
	v_mfma_f32_32x32x16_bf16 a[96:111], v[0:3], v[18:21], a[96:111]
	s_waitcnt lgkmcnt(0)
	v_mfma_f32_32x32x16_bf16 a[32:47], v[0:3], v[124:127], a[32:47]
	ds_read_b128 v[0:3], v9 offset:4096
	s_waitcnt lgkmcnt(0)
	v_mfma_f32_32x32x16_bf16 a[192:207], v[0:3], v[4:7], a[192:207]
	v_mfma_f32_32x32x16_bf16 a[128:143], v[0:3], v[14:17], a[128:143]
	v_mfma_f32_32x32x16_bf16 a[64:79], v[0:3], v[18:21], a[64:79]
	v_mfma_f32_32x32x16_bf16 a[0:15], v[0:3], v[124:127], a[0:15]
	ds_read_b128 v[0:3], v9 offset:16384
	s_waitcnt lgkmcnt(0)
	v_mfma_f32_32x32x16_bf16 a[240:255], v[0:3], v[4:7], a[240:255]
	v_mfma_f32_32x32x16_bf16 a[208:223], v[36:39], v[4:7], a[208:223]
	v_lshlrev_b32_e32 v4, 1, v13
	v_add3_u32 v9, v10, v4, s4
	v_add3_u32 v4, v8, v4, s5
	ds_read_b128 v[40:43], v4
	ds_read_b128 v[32:35], v4 offset:4096
	ds_read_b128 v[140:143], v4 offset:8192
	ds_read_b128 v[180:183], v4 offset:12288
	v_mfma_f32_32x32x16_bf16 a[176:191], v[0:3], v[14:17], a[176:191]
	v_lshlrev_b32_e32 v4, 1, v12
	v_mfma_f32_32x32x16_bf16 a[112:127], v[0:3], v[18:21], a[112:127]
	v_mfma_f32_32x32x16_bf16 a[48:63], v[0:3], v[124:127], a[48:63]
	ds_read_b128 v[0:3], v9
	v_mfma_f32_32x32x16_bf16 a[144:159], v[36:39], v[14:17], a[144:159]
	v_add3_u32 v16, v10, v4, s4
	v_add3_u32 v10, v10, v11, s4
	v_add3_u32 v17, v8, v4, s5
	ds_read_b128 v[4:7], v10
	ds_read_b128 v[48:51], v17
	s_mov_b32 s4, 0
	s_waitcnt lgkmcnt(2)
	v_mfma_f32_32x32x16_bf16 a[224:239], v[0:3], v[40:43], a[224:239]
	v_mfma_f32_32x32x16_bf16 a[160:175], v[0:3], v[32:35], a[160:175]
	v_mfma_f32_32x32x16_bf16 a[96:111], v[0:3], v[140:143], a[96:111]
	v_mfma_f32_32x32x16_bf16 a[32:47], v[0:3], v[180:183], a[32:47]
	ds_read_b128 v[0:3], v9 offset:4096
	s_waitcnt lgkmcnt(0)
	v_mfma_f32_32x32x16_bf16 a[192:207], v[0:3], v[40:43], a[192:207]
	v_mfma_f32_32x32x16_bf16 a[128:143], v[0:3], v[32:35], a[128:143]
	v_mfma_f32_32x32x16_bf16 a[64:79], v[0:3], v[140:143], a[64:79]
	v_mfma_f32_32x32x16_bf16 a[0:15], v[0:3], v[180:183], a[0:15]
	ds_read_b128 v[0:3], v9 offset:16384
	s_waitcnt lgkmcnt(0)
	v_mfma_f32_32x32x16_bf16 a[240:255], v[0:3], v[40:43], a[240:255]
	v_mfma_f32_32x32x16_bf16 a[176:191], v[0:3], v[32:35], a[176:191]
	v_mfma_f32_32x32x16_bf16 a[112:127], v[0:3], v[140:143], a[112:127]
	v_mfma_f32_32x32x16_bf16 a[48:63], v[0:3], v[180:183], a[48:63]
	ds_read_b128 v[0:3], v16
	v_mfma_f32_32x32x16_bf16 a[80:95], v[36:39], v[18:21], a[80:95]
	v_add3_u32 v18, v8, v11, s5
	ds_read_b128 v[44:47], v18
	ds_read_b128 v[28:31], v9 offset:20480
	ds_read_b128 v[12:15], v16 offset:4096
	ds_read_b128 v[64:67], v17 offset:4096
	ds_read_b128 v[68:71], v16 offset:16384
	ds_read_b128 v[238:241], v16 offset:20480
	ds_read_b128 v[52:55], v17 offset:8192
	ds_read_b128 v[248:251], v17 offset:12288
	ds_read_b128 v[82:85], v10 offset:4096
	ds_read_b128 v[60:63], v18 offset:4096
	ds_read_b128 v[72:75], v10 offset:16384
	ds_read_b128 v[8:11], v10 offset:20480
	ds_read_b128 v[56:59], v18 offset:8192
	ds_read_b128 v[20:23], v18 offset:12288
	s_waitcnt vmcnt(0)
	s_waitcnt lgkmcnt(0)
	s_barrier
	v_mfma_f32_32x32x16_bf16 a[224:239], v[0:3], v[48:51], a[224:239]
	s_mov_b32 s5, 0
	v_mfma_f32_32x32x16_bf16 a[160:175], v[0:3], v[64:67], a[160:175]
	v_mfma_f32_32x32x16_bf16 a[96:111], v[0:3], v[52:55], a[96:111]
	v_mfma_f32_32x32x16_bf16 a[32:47], v[0:3], v[248:251], a[32:47]
	v_mfma_f32_32x32x16_bf16 a[240:255], v[68:71], v[48:51], a[240:255]
	v_mfma_f32_32x32x16_bf16 a[176:191], v[68:71], v[64:67], a[176:191]
	v_mfma_f32_32x32x16_bf16 a[112:127], v[68:71], v[52:55], a[112:127]
	v_mfma_f32_32x32x16_bf16 a[48:63], v[68:71], v[248:251], a[48:63]
	v_mfma_f32_32x32x16_bf16 a[224:239], v[4:7], v[44:47], a[224:239]
	v_mfma_f32_32x32x16_bf16 a[160:175], v[4:7], v[60:63], a[160:175]
	s_nop 10
	v_accvgpr_read_b32 v117, a227
	v_accvgpr_read_b32 v116, a226
	v_accvgpr_read_b32 v103, a229
	v_mfma_f32_32x32x16_bf16 a[96:111], v[4:7], v[56:59], a[96:111]
	v_accvgpr_read_b32 v102, a228
	v_accvgpr_read_b32 v227, a239
	v_accvgpr_read_b32 v226, a238
	v_accvgpr_read_b32 v229, a237
	v_accvgpr_read_b32 v228, a236
	v_accvgpr_read_b32 v253, a235
	v_accvgpr_read_b32 v252, a234
	v_mfma_f32_32x32x16_bf16 a[32:47], v[4:7], v[20:23], a[32:47]
	v_mbcnt_lo_u32_b32 v4, -1, s4
	v_mbcnt_hi_u32_b32 v16, -1, v4
	v_or_b32_e32 v4, s60, v16
	v_and_b32_e32 v5, 31, v16
	v_lshrrev_b32_e32 v16, 3, v16
	s_and_b32 s4, s10, 3
	s_cmp_gt_i32 s10, 3
	v_mfma_f32_32x32x16_bf16 a[192:207], v[12:15], v[48:51], a[192:207]
	s_cselect_b64 vcc, -1, 0
	v_accvgpr_read_b32 v81, a233
	v_accvgpr_read_b32 v80, a232
	v_accvgpr_read_b32 v79, a231
	v_accvgpr_read_b32 v99, a39
	v_accvgpr_read_b32 v98, a38
	v_accvgpr_read_b32 v129, a35
	v_mfma_f32_32x32x16_bf16 a[128:143], v[12:15], v[64:67], a[128:143]
	v_accvgpr_read_b32 v128, a34
	v_accvgpr_read_b32 v78, a230
	v_accvgpr_read_b32 v131, a175
	v_accvgpr_read_b32 v130, a174
	v_accvgpr_read_b32 v133, a173
	v_accvgpr_read_b32 v132, a172
	v_accvgpr_read_b32 v111, a171
	v_mfma_f32_32x32x16_bf16 a[64:79], v[12:15], v[52:55], a[64:79]
	v_accvgpr_read_b32 v110, a170
	v_accvgpr_read_b32 v113, a169
	v_accvgpr_read_b32 v112, a168
	v_accvgpr_read_b32 v135, a167
	v_accvgpr_read_b32 v134, a166
	v_accvgpr_read_b32 v121, a165
	v_accvgpr_read_b32 v120, a164
	v_mfma_f32_32x32x16_bf16 a[0:15], v[12:15], v[248:251], a[0:15]
	v_lshlrev_b32_e32 v12, 1, v4
	v_ashrrev_i32_e32 v4, 1, v4
	v_and_b32_e32 v24, 0xffffffc0, v4
	v_ashrrev_i32_e32 v25, 31, v24
	v_accvgpr_read_b32 v109, a163
	v_accvgpr_read_b32 v108, a162
	v_accvgpr_read_b32 v209, a111
	v_mfma_f32_32x32x16_bf16 a[240:255], v[72:75], v[44:47], a[240:255]
	v_accvgpr_read_b32 v208, a110
	v_accvgpr_read_b32 v213, a109
	v_accvgpr_read_b32 v212, a108
	v_accvgpr_read_b32 v219, a107
	v_accvgpr_read_b32 v218, a106
	v_accvgpr_read_b32 v221, a105
	v_accvgpr_read_b32 v220, a104
	v_mfma_f32_32x32x16_bf16 a[176:191], v[72:75], v[60:63], a[176:191]
	v_accvgpr_read_b32 v203, a103
	v_accvgpr_read_b32 v202, a102
	v_accvgpr_read_b32 v205, a101
	v_accvgpr_read_b32 v204, a100
	v_accvgpr_read_b32 v139, a243
	v_accvgpr_read_b32 v138, a242
	v_accvgpr_read_b32 v123, a245
	v_mfma_f32_32x32x16_bf16 a[112:127], v[72:75], v[56:59], a[112:127]
	v_accvgpr_read_b32 v122, a244
	v_accvgpr_read_b32 v173, a99
	v_accvgpr_read_b32 v172, a98
	v_accvgpr_read_b32 v89, a47
	v_accvgpr_read_b32 v88, a46
	v_accvgpr_read_b32 v91, a45
	v_accvgpr_read_b32 v90, a44
	v_mfma_f32_32x32x16_bf16 a[48:63], v[72:75], v[20:23], a[48:63]
	v_and_or_b32 v74, v12, s14, v5
	v_lshlrev_b64 v[4:5], 2, v[24:25]
	v_and_b32_e32 v25, 4, v16
	v_lshl_add_u64 v[12:13], s[0:1], 0, v[4:5]
	v_lshlrev_b32_e32 v94, 2, v25
	v_lshl_add_u64 v[4:5], s[6:7], 0, v[4:5]
	v_lshl_add_u64 v[186:187], v[4:5], 0, v[94:95]
	v_or_b32_e32 v4, s66, v74
	v_lshl_add_u64 v[184:185], v[12:13], 0, v[94:95]
	v_lshlrev_b32_e32 v94, 9, v4
	v_mfma_f32_32x32x16_bf16 a[144:159], v[28:31], v[32:35], a[144:159]
	v_lshl_add_u64 v[68:69], v[186:187], 0, v[94:95]
	v_lshl_add_u64 v[72:73], v[184:185], 0, v[94:95]
	global_load_dwordx4 v[32:35], v[68:69], off
	v_or_b32_e32 v24, v24, v25
	v_accvgpr_read_b32 v87, a43
	v_accvgpr_read_b32 v86, a42
	v_accvgpr_read_b32 v97, a41
	v_mfma_f32_32x32x16_bf16 a[208:223], v[28:31], v[40:43], a[208:223]
	global_load_dwordx4 v[40:43], v[72:73], off
	v_accvgpr_read_b32 v96, a40
	v_accvgpr_read_b32 v107, a37
	v_accvgpr_read_b32 v106, a36
	v_accvgpr_read_b32 v3, a253
	v_accvgpr_read_b32 v2, a252
	v_accvgpr_read_b32 v7, a249
	v_mfma_f32_32x32x16_bf16 a[144:159], v[238:241], v[64:67], a[144:159]
	global_load_dwordx4 v[64:67], v[68:69], off offset:32
	global_load_dwordx4 v[16:19], v[72:73], off offset:32
	v_accvgpr_read_b32 v6, a248
	v_accvgpr_read_b32 v15, a247
	v_accvgpr_read_b32 v14, a246
	v_accvgpr_read_b32 v147, a191
	v_accvgpr_read_b32 v146, a190
	v_accvgpr_read_b32 v155, a189
	v_mfma_f32_32x32x16_bf16 a[16:31], v[36:39], v[124:127], a[16:31]
	v_accvgpr_read_b32 v154, a188
	v_accvgpr_read_b32 v153, a187
	v_accvgpr_read_b32 v152, a186
	v_accvgpr_read_b32 v137, a185
	v_accvgpr_read_b32 v136, a184
	v_accvgpr_read_b32 v165, a183
	v_accvgpr_read_b32 v164, a182
	v_mfma_f32_32x32x16_bf16 a[80:95], v[28:31], v[140:143], a[80:95]
	v_accvgpr_read_b32 v207, a181
	v_accvgpr_read_b32 v206, a180
	v_accvgpr_read_b32 v71, a179
	v_accvgpr_read_b32 v70, a178
	v_accvgpr_read_b32 v243, a127
	v_accvgpr_read_b32 v242, a126
	v_accvgpr_read_b32 v245, a125
	v_mfma_f32_32x32x16_bf16 a[16:31], v[28:31], v[180:183], a[16:31]
	v_mov_b32_e32 v30, 0x3d800000
	v_accvgpr_read_b32 v244, a124
	v_accvgpr_read_b32 v247, a123
	v_accvgpr_read_b32 v246, a122
	v_accvgpr_read_b32 v237, a121
	v_accvgpr_read_b32 v236, a120
	v_accvgpr_read_b32 v225, a119
	v_mfma_f32_32x32x16_bf16 a[208:223], v[238:241], v[48:51], a[208:223]
	v_cndmask_b32_e32 v50, 1.0, v30, vcc
	v_accvgpr_read_b32 v224, a118
	v_accvgpr_read_b32 v233, a117
	v_accvgpr_read_b32 v232, a116
	v_accvgpr_read_b32 v217, a115
	v_accvgpr_read_b32 v216, a114
	v_accvgpr_read_b32 v125, a63
	v_mfma_f32_32x32x16_bf16 a[80:95], v[238:241], v[52:55], a[80:95]
	v_accvgpr_read_b32 v124, a62
	v_accvgpr_read_b32 v127, a61
	v_accvgpr_read_b32 v126, a60
	v_accvgpr_read_b32 v141, a59
	v_accvgpr_read_b32 v140, a58
	v_accvgpr_read_b32 v143, a57
	v_accvgpr_read_b32 v142, a56
	v_mfma_f32_32x32x16_bf16 a[16:31], v[238:241], v[248:251], a[16:31]
	v_accvgpr_read_b32 v161, a55
	v_accvgpr_read_b32 v160, a54
	v_accvgpr_read_b32 v167, a53
	v_accvgpr_read_b32 v166, a52
	v_accvgpr_read_b32 v193, a51
	v_accvgpr_read_b32 v192, a50
	v_accvgpr_read_b32 v77, a255
	v_mfma_f32_32x32x16_bf16 a[0:15], v[82:85], v[20:23], a[0:15]
	v_accvgpr_read_b32 v76, a254
	s_waitcnt vmcnt(3)
	v_mul_f32_e64 v26, v116, v34
	v_mul_f32_e64 v27, v117, v35
	v_mfma_f32_32x32x16_bf16 a[208:223], v[8:11], v[44:47], a[208:223]
	s_nop 6
	v_accvgpr_read_b32 v1, a15
	v_accvgpr_read_b32 v0, a14
	v_accvgpr_write_b32 a15, v1
	v_accvgpr_write_b32 a14, v0
	s_waitcnt vmcnt(2)
	v_pk_fma_f32 v[26:27], v[138:139], v[42:43], v[26:27]
	v_accvgpr_read_b32 v1, a13
	v_accvgpr_read_b32 v0, a12
	v_mfma_f32_32x32x16_bf16 a[144:159], v[8:11], v[60:63], a[144:159]
	v_accvgpr_write_b32 a13, v1
	v_accvgpr_write_b32 a12, v0
	v_accvgpr_read_b32 v1, a9
	v_accvgpr_read_b32 v0, a8
	v_accvgpr_write_b32 a39, v1
	v_accvgpr_read_b32 v93, a3
	v_accvgpr_read_b32 v92, a2
	v_mfma_f32_32x32x16_bf16 a[80:95], v[8:11], v[56:59], a[80:95]
	v_accvgpr_write_b32 a38, v0
	v_accvgpr_read_b32 v1, a251
	v_accvgpr_read_b32 v0, a250
	v_accvgpr_read_b32 v49, a219
	v_accvgpr_read_b32 v48, a218
	v_accvgpr_read_b32 v37, a215
	v_accvgpr_read_b32 v36, a214
	v_mfma_f32_32x32x16_bf16 a[16:31], v[8:11], v[20:23], a[16:31]
	v_accvgpr_read_b32 v10, a240
	v_accvgpr_read_b32 v8, a224
	v_accvgpr_read_b32 v11, a241
	v_accvgpr_read_b32 v9, a225
	v_mul_f32_e64 v20, v10, v32
	v_mul_f32_e64 v21, v11, v33
	v_pk_mul_f32 v[22:23], v[138:139], v[34:35]
	v_pk_fma_f32 v[20:21], v[8:9], v[40:41], v[20:21] neg_lo:[0,0,1] neg_hi:[0,0,1]
	v_mfma_f32_32x32x16_bf16 a[192:207], v[82:85], v[44:47], a[192:207]
	v_mul_f32_e64 v8, v8, v32
	v_mul_f32_e64 v9, v9, v33
	v_fma_f32 v22, v116, v42, -v22
	v_fma_f32 v23, v117, v43, -v23
	v_fma_f32 v8, v10, v40, v8
	v_fma_f32 v9, v11, v41, v9
	v_pk_mul_f32 v[32:33], v[50:51], v[20:21] op_sel_hi:[0,1]
	v_pk_mul_f32 v[20:21], v[50:51], v[8:9] op_sel_hi:[0,1]
	v_pk_mul_f32 v[30:31], v[50:51], v[22:23] op_sel_hi:[0,1]
	v_pk_mul_f32 v[22:23], v[50:51], v[26:27] op_sel_hi:[0,1]
	v_mfma_f32_32x32x16_bf16 a[128:143], v[82:85], v[60:63], a[128:143]
	v_lshlrev_b32_e32 v51, 1, v24
	v_cvt_pk_bf16_f32 v8, v32, v33
	v_cvt_pk_bf16_f32 v9, v30, v31
	v_mad_u32_u24 v75, v74, s25, v51
	v_accvgpr_read_b32 v47, a31
	v_accvgpr_read_b32 v46, a30
	v_accvgpr_write_b32 a35, v33
	v_mfma_f32_32x32x16_bf16 a[64:79], v[82:85], v[56:59], a[64:79]
	v_accvgpr_read_b32 v83, a5
	v_accvgpr_read_b32 v82, a4
	v_accvgpr_write_b32 a4, v20
	v_accvgpr_write_b32 a5, v21
	v_cvt_pk_bf16_f32 v20, v20, v21
	v_cvt_pk_bf16_f32 v21, v22, v23
	ds_write2_b64 v75, v[8:9], v[20:21] offset1:32
	s_waitcnt vmcnt(1)
	v_pk_mul_f32 v[8:9], v[122:123], v[64:65]
	v_accvgpr_write_b32 a30, v30
	s_waitcnt vmcnt(0)
	v_pk_fma_f32 v[20:21], v[102:103], v[16:17], v[8:9] neg_lo:[0,0,1] neg_hi:[0,0,1]
	v_pk_mul_f32 v[8:9], v[102:103], v[64:65]
	v_accvgpr_write_b32 a2, v22
	v_pk_fma_f32 v[16:17], v[122:123], v[16:17], v[8:9]
	v_accvgpr_read_b32 v169, a207
	v_accvgpr_read_b32 v168, a206
	v_accvgpr_read_b32 v119, a205
	v_accvgpr_read_b32 v118, a204
	v_accvgpr_read_b32 v115, a203
	v_accvgpr_read_b32 v114, a202
	v_accvgpr_read_b32 v105, a201
	v_accvgpr_read_b32 v104, a200
	v_accvgpr_read_b32 v101, a199
	v_accvgpr_read_b32 v100, a198
	v_accvgpr_read_b32 v211, a197
	v_accvgpr_read_b32 v210, a196
	v_accvgpr_read_b32 v235, a195
	v_accvgpr_read_b32 v234, a194
	v_accvgpr_read_b32 v175, a143
	v_accvgpr_read_b32 v174, a142
	v_accvgpr_read_b32 v195, a141
	v_accvgpr_read_b32 v194, a140
	v_accvgpr_read_b32 v177, a139
	v_accvgpr_read_b32 v176, a138
	v_accvgpr_read_b32 v179, a137
	v_accvgpr_read_b32 v178, a136
	v_accvgpr_read_b32 v157, a135
	v_accvgpr_read_b32 v156, a134
	v_accvgpr_read_b32 v159, a133
	v_accvgpr_read_b32 v158, a132
	v_accvgpr_read_b32 v145, a131
	v_accvgpr_read_b32 v144, a130
	v_accvgpr_read_b32 v149, a79
	v_accvgpr_read_b32 v148, a78
	v_accvgpr_read_b32 v151, a77
	v_accvgpr_read_b32 v150, a76
	v_accvgpr_read_b32 v163, a75
	v_accvgpr_read_b32 v162, a74
	v_accvgpr_read_b32 v171, a73
	v_accvgpr_read_b32 v170, a72
	v_accvgpr_read_b32 v189, a71
	v_accvgpr_read_b32 v188, a70
	v_accvgpr_read_b32 v191, a69
	v_accvgpr_read_b32 v190, a68
	v_accvgpr_read_b32 v215, a67
	v_accvgpr_read_b32 v214, a66
	v_accvgpr_read_b32 v85, a7
	v_accvgpr_read_b32 v84, a6
	v_accvgpr_read_b32 v45, a223
	v_accvgpr_read_b32 v44, a222
	v_accvgpr_read_b32 v63, a217
	v_accvgpr_read_b32 v62, a216
	v_accvgpr_read_b32 v39, a213
	v_accvgpr_read_b32 v38, a212
	v_accvgpr_read_b32 v29, a211
	v_accvgpr_read_b32 v28, a210
	v_accvgpr_read_b32 v197, a157
	v_accvgpr_read_b32 v196, a156
	v_accvgpr_read_b32 v5, a155
	v_accvgpr_read_b32 v4, a154
	v_accvgpr_read_b32 v199, a153
	v_accvgpr_read_b32 v198, a152
	v_accvgpr_read_b32 v201, a151
	v_accvgpr_read_b32 v200, a150
	v_accvgpr_read_b32 v183, a149
	v_accvgpr_read_b32 v182, a148
	v_accvgpr_read_b32 v181, a147
	v_accvgpr_read_b32 v180, a146
	v_accvgpr_read_b32 v223, a95
	v_accvgpr_read_b32 v222, a94
	v_accvgpr_read_b32 v231, a93
	v_accvgpr_read_b32 v230, a92
	v_accvgpr_read_b32 v239, a91
	v_accvgpr_read_b32 v238, a90
	v_accvgpr_read_b32 v241, a89
	v_accvgpr_read_b32 v240, a88
	v_accvgpr_read_b32 v249, a87
	v_accvgpr_read_b32 v248, a86
	v_accvgpr_read_b32 v251, a85
	v_accvgpr_read_b32 v250, a84
	v_accvgpr_write_b32 a34, v32
	v_accvgpr_write_b32 a31, v31
	v_accvgpr_write_b32 a3, v23
	v_accvgpr_read_b32 v57, a29
	v_accvgpr_read_b32 v56, a28
	v_accvgpr_read_b32 v8, a26
	v_accvgpr_read_b32 v103, a25
	v_accvgpr_read_b32 v102, a24
	v_accvgpr_read_b32 v117, a23
	v_accvgpr_read_b32 v116, a22
	v_accvgpr_read_b32 v123, a21
	v_accvgpr_read_b32 v122, a20
	v_accvgpr_read_b32 v139, a19
	v_accvgpr_read_b32 v138, a18
	v_pk_mul_f32 v[24:25], v[50:51], v[20:21] op_sel_hi:[0,1]
	v_pk_mul_f32 v[20:21], v[50:51], v[16:17] op_sel_hi:[0,1]
	v_accvgpr_mov_b32 a37, a11
	v_accvgpr_mov_b32 a36, a10
	v_accvgpr_read_b32 v61, a221
	v_accvgpr_read_b32 v60, a220
	v_accvgpr_read_b32 v13, a159
	v_accvgpr_read_b32 v12, a158
	v_accvgpr_read_b32 v11, a83
	v_accvgpr_read_b32 v10, a82
	v_accvgpr_read_b32 v9, a27
	v_pk_mul_f32 v[16:17], v[14:15], v[66:67]
	v_accvgpr_write_b32 a8, v20
	v_pk_fma_f32 v[16:17], v[78:79], v[18:19], v[16:17] neg_lo:[0,0,1] neg_hi:[0,0,1]
	v_accvgpr_write_b32 a9, v21
	v_pk_mul_f32 v[22:23], v[50:51], v[16:17] op_sel_hi:[0,1]
	v_pk_mul_f32 v[16:17], v[78:79], v[66:67]
	v_accvgpr_write_b32 a22, v24
	v_pk_fma_f32 v[14:15], v[14:15], v[18:19], v[16:17]
	v_cvt_pk_bf16_f32 v16, v20, v21
	v_pk_mul_f32 v[18:19], v[50:51], v[14:15] op_sel_hi:[0,1]
	v_cvt_pk_bf16_f32 v14, v24, v25
	v_cvt_pk_bf16_f32 v15, v22, v23
	v_cvt_pk_bf16_f32 v17, v18, v19
	v_accvgpr_write_b32 a6, v18
	ds_write2_b64 v75, v[14:15], v[16:17] offset0:2 offset1:34
	v_accvgpr_write_b32 a7, v19
	global_load_dwordx4 v[18:21], v[72:73], off offset:64
	global_load_dwordx4 v[30:33], v[68:69], off offset:64
	v_accvgpr_write_b32 a23, v25
	v_accvgpr_write_b32 a20, v22
	v_accvgpr_write_b32 a21, v23
	s_waitcnt vmcnt(0)
	v_pk_mul_f32 v[14:15], v[6:7], v[30:31]
	s_nop 0
	v_pk_fma_f32 v[14:15], v[80:81], v[18:19], v[14:15] neg_lo:[0,0,1] neg_hi:[0,0,1]
	s_nop 0
	v_pk_mul_f32 v[24:25], v[50:51], v[14:15] op_sel_hi:[0,1]
	v_pk_mul_f32 v[14:15], v[80:81], v[30:31]
	s_nop 0
	v_pk_fma_f32 v[6:7], v[6:7], v[18:19], v[14:15]
	s_nop 0
	v_pk_mul_f32 v[16:17], v[50:51], v[6:7] op_sel_hi:[0,1]
	v_pk_mul_f32 v[6:7], v[0:1], v[32:33]
	v_accvgpr_write_b32 a19, v17
	v_pk_fma_f32 v[6:7], v[252:253], v[20:21], v[6:7] neg_lo:[0,0,1] neg_hi:[0,0,1]
	v_accvgpr_write_b32 a18, v16
	v_pk_mul_f32 v[26:27], v[50:51], v[6:7] op_sel_hi:[0,1]
	v_pk_mul_f32 v[6:7], v[252:253], v[32:33]
	s_nop 0
	v_pk_fma_f32 v[0:1], v[0:1], v[20:21], v[6:7]
	v_cvt_pk_bf16_f32 v6, v16, v17
	v_pk_mul_f32 v[14:15], v[50:51], v[0:1] op_sel_hi:[0,1]
	v_cvt_pk_bf16_f32 v0, v24, v25
	v_cvt_pk_bf16_f32 v1, v26, v27
	v_cvt_pk_bf16_f32 v7, v14, v15
	ds_write2_b64 v75, v[0:1], v[6:7] offset0:4 offset1:36
	global_load_dwordx4 v[18:21], v[72:73], off offset:96
	global_load_dwordx4 v[40:43], v[68:69], off offset:96
	v_accvgpr_write_b32 a10, v14
	v_accvgpr_write_b32 a11, v15
	s_waitcnt vmcnt(0)
	v_pk_mul_f32 v[0:1], v[2:3], v[40:41]
	s_nop 0
	v_pk_fma_f32 v[0:1], v[228:229], v[18:19], v[0:1] neg_lo:[0,0,1] neg_hi:[0,0,1]
	s_nop 0
	v_pk_mul_f32 v[32:33], v[50:51], v[0:1] op_sel_hi:[0,1]
	v_pk_mul_f32 v[0:1], v[228:229], v[40:41]
	s_nop 0
	v_pk_fma_f32 v[0:1], v[2:3], v[18:19], v[0:1]
	s_nop 0
	v_pk_mul_f32 v[22:23], v[50:51], v[0:1] op_sel_hi:[0,1]
	v_pk_mul_f32 v[0:1], v[76:77], v[42:43]
	v_cvt_pk_bf16_f32 v2, v22, v23
	v_pk_fma_f32 v[0:1], v[226:227], v[20:21], v[0:1] neg_lo:[0,0,1] neg_hi:[0,0,1]
	v_accvgpr_read_b32 v14, a208
	v_pk_mul_f32 v[34:35], v[50:51], v[0:1] op_sel_hi:[0,1]
	v_pk_mul_f32 v[0:1], v[226:227], v[42:43]
	v_accvgpr_read_b32 v15, a209
	v_pk_fma_f32 v[0:1], v[76:77], v[20:21], v[0:1]
	s_nop 0
	v_pk_mul_f32 v[6:7], v[50:51], v[0:1] op_sel_hi:[0,1]
	v_cvt_pk_bf16_f32 v0, v32, v33
	v_cvt_pk_bf16_f32 v1, v34, v35
	v_cvt_pk_bf16_f32 v3, v6, v7
	ds_write2_b64 v75, v[0:1], v[2:3] offset0:6 offset1:38
	global_load_dwordx4 v[0:3], v[72:73], off offset:128
	global_load_dwordx4 v[52:55], v[68:69], off offset:128
	v_accvgpr_write_b32 a25, v7
	v_accvgpr_write_b32 a24, v6
	v_accvgpr_read_b32 v6, a192
	v_accvgpr_read_b32 v7, a193
	s_waitcnt vmcnt(0)
	v_pk_mul_f32 v[16:17], v[14:15], v[52:53]
	s_nop 0
	v_pk_fma_f32 v[16:17], v[6:7], v[0:1], v[16:17] neg_lo:[0,0,1] neg_hi:[0,0,1]
	v_pk_mul_f32 v[6:7], v[6:7], v[52:53]
	v_pk_mul_f32 v[40:41], v[50:51], v[16:17] op_sel_hi:[0,1]
	v_pk_fma_f32 v[0:1], v[14:15], v[0:1], v[6:7]
	s_nop 0
	v_pk_mul_f32 v[30:31], v[50:51], v[0:1] op_sel_hi:[0,1]
	v_pk_mul_f32 v[0:1], v[28:29], v[54:55]
	s_nop 0
	v_pk_fma_f32 v[0:1], v[234:235], v[2:3], v[0:1] neg_lo:[0,0,1] neg_hi:[0,0,1]
	s_nop 0
	v_pk_mul_f32 v[42:43], v[50:51], v[0:1] op_sel_hi:[0,1]
	v_pk_mul_f32 v[0:1], v[234:235], v[54:55]
	s_nop 0
	v_pk_fma_f32 v[0:1], v[28:29], v[2:3], v[0:1]
	v_cvt_pk_bf16_f32 v2, v30, v31
	v_pk_mul_f32 v[28:29], v[50:51], v[0:1] op_sel_hi:[0,1]
	v_cvt_pk_bf16_f32 v0, v40, v41
	v_cvt_pk_bf16_f32 v1, v42, v43
	v_cvt_pk_bf16_f32 v3, v28, v29
	ds_write2_b64 v75, v[0:1], v[2:3] offset0:8 offset1:40
	global_load_dwordx4 v[0:3], v[72:73], off offset:160
	global_load_dwordx4 v[52:55], v[68:69], off offset:160
	s_waitcnt vmcnt(0)
	v_pk_mul_f32 v[6:7], v[38:39], v[52:53]
	s_nop 0
	v_pk_fma_f32 v[6:7], v[210:211], v[0:1], v[6:7] neg_lo:[0,0,1] neg_hi:[0,0,1]
	s_nop 0
	v_pk_mul_f32 v[58:59], v[50:51], v[6:7] op_sel_hi:[0,1]
	v_pk_mul_f32 v[6:7], v[210:211], v[52:53]
	s_nop 0
	v_pk_fma_f32 v[0:1], v[38:39], v[0:1], v[6:7]
	s_nop 0
	v_pk_mul_f32 v[38:39], v[50:51], v[0:1] op_sel_hi:[0,1]
	v_pk_mul_f32 v[0:1], v[36:37], v[54:55]
	s_nop 0
	v_pk_fma_f32 v[0:1], v[100:101], v[2:3], v[0:1] neg_lo:[0,0,1] neg_hi:[0,0,1]
	s_nop 0
	v_pk_mul_f32 v[14:15], v[50:51], v[0:1] op_sel_hi:[0,1]
	v_pk_mul_f32 v[0:1], v[100:101], v[54:55]
	s_nop 0
	v_pk_fma_f32 v[0:1], v[36:37], v[2:3], v[0:1]
	v_cvt_pk_bf16_f32 v2, v38, v39
	v_pk_mul_f32 v[36:37], v[50:51], v[0:1] op_sel_hi:[0,1]
	v_cvt_pk_bf16_f32 v0, v58, v59
	v_cvt_pk_bf16_f32 v1, v14, v15
	v_cvt_pk_bf16_f32 v3, v36, v37
	ds_write2_b64 v75, v[0:1], v[2:3] offset0:10 offset1:42
	global_load_dwordx4 v[0:3], v[72:73], off offset:192
	global_load_dwordx4 v[64:67], v[68:69], off offset:192
	s_waitcnt vmcnt(0)
	v_pk_mul_f32 v[6:7], v[62:63], v[64:65]
	s_nop 0
	v_pk_fma_f32 v[6:7], v[104:105], v[0:1], v[6:7] neg_lo:[0,0,1] neg_hi:[0,0,1]
	s_nop 0
	v_pk_mul_f32 v[100:101], v[50:51], v[6:7] op_sel_hi:[0,1]
	v_pk_mul_f32 v[6:7], v[104:105], v[64:65]
	s_nop 0
	v_pk_fma_f32 v[0:1], v[62:63], v[0:1], v[6:7]
	s_nop 0
	v_pk_mul_f32 v[54:55], v[50:51], v[0:1] op_sel_hi:[0,1]
	v_pk_mul_f32 v[0:1], v[48:49], v[66:67]
	s_nop 0
	v_pk_fma_f32 v[0:1], v[114:115], v[2:3], v[0:1] neg_lo:[0,0,1] neg_hi:[0,0,1]
	s_nop 0
	v_pk_mul_f32 v[104:105], v[50:51], v[0:1] op_sel_hi:[0,1]
	v_pk_mul_f32 v[0:1], v[114:115], v[66:67]
	s_nop 0
	v_pk_fma_f32 v[0:1], v[48:49], v[2:3], v[0:1]
	v_cvt_pk_bf16_f32 v2, v54, v55
	v_pk_mul_f32 v[52:53], v[50:51], v[0:1] op_sel_hi:[0,1]
	v_cvt_pk_bf16_f32 v0, v100, v101
	v_cvt_pk_bf16_f32 v1, v104, v105
	v_cvt_pk_bf16_f32 v3, v52, v53
	ds_write2_b64 v75, v[0:1], v[2:3] offset0:12 offset1:44
	global_load_dwordx4 v[0:3], v[72:73], off offset:224
	global_load_dwordx4 v[64:67], v[68:69], off offset:224
	s_waitcnt vmcnt(0)
	v_pk_mul_f32 v[6:7], v[60:61], v[64:65]
	s_nop 0
	v_pk_fma_f32 v[6:7], v[118:119], v[0:1], v[6:7] neg_lo:[0,0,1] neg_hi:[0,0,1]
	s_nop 0
	v_pk_mul_f32 v[114:115], v[50:51], v[6:7] op_sel_hi:[0,1]
	v_pk_mul_f32 v[6:7], v[118:119], v[64:65]
	s_nop 0
	v_pk_fma_f32 v[0:1], v[60:61], v[0:1], v[6:7]
	s_nop 0
	v_pk_mul_f32 v[64:65], v[50:51], v[0:1] op_sel_hi:[0,1]
	v_pk_mul_f32 v[0:1], v[44:45], v[66:67]
	s_nop 0
	v_pk_fma_f32 v[0:1], v[168:169], v[2:3], v[0:1] neg_lo:[0,0,1] neg_hi:[0,0,1]
	s_nop 0
	v_pk_mul_f32 v[118:119], v[50:51], v[0:1] op_sel_hi:[0,1]
	v_pk_mul_f32 v[0:1], v[168:169], v[66:67]
	s_nop 0
	v_pk_fma_f32 v[0:1], v[44:45], v[2:3], v[0:1]
	v_cvt_pk_bf16_f32 v2, v64, v65
	v_pk_mul_f32 v[66:67], v[50:51], v[0:1] op_sel_hi:[0,1]
	v_cvt_pk_bf16_f32 v0, v114, v115
	v_cvt_pk_bf16_f32 v1, v118, v119
	v_cvt_pk_bf16_f32 v3, v66, v67
	ds_write2_b64 v75, v[0:1], v[2:3] offset0:14 offset1:46
	v_or_b32_e32 v60, 32, v74
	v_or_b32_e32 v0, s66, v60
	v_lshlrev_b32_e32 v94, 9, v0
	v_lshl_add_u64 v[76:77], v[184:185], 0, v[94:95]
	v_lshl_add_u64 v[6:7], v[186:187], 0, v[94:95]
	global_load_dwordx4 a[192:195], v[76:77], off
	global_load_dwordx4 a[196:199], v[6:7], off
	global_load_dwordx4 a[200:203], v[76:77], off offset:32
	global_load_dwordx4 a[204:207], v[6:7], off offset:32
	global_load_dwordx4 a[208:211], v[76:77], off offset:64
	global_load_dwordx4 a[212:215], v[6:7], off offset:64
	global_load_dwordx4 a[216:219], v[76:77], off offset:96
	global_load_dwordx4 a[220:223], v[6:7], off offset:96
	global_load_dwordx4 a[224:227], v[76:77], off offset:128
	global_load_dwordx4 a[228:231], v[6:7], off offset:128
	global_load_dwordx4 a[232:235], v[76:77], off offset:160
	global_load_dwordx4 a[236:239], v[6:7], off offset:160
	global_load_dwordx4 a[240:243], v[76:77], off offset:192
	global_load_dwordx4 a[244:247], v[6:7], off offset:192
	global_load_dwordx4 a[248:251], v[76:77], off offset:224
	global_load_dwordx4 a[252:255], v[6:7], off offset:224
	v_accvgpr_read_b32 v18, a176
	v_accvgpr_read_b32 v16, a160
	v_accvgpr_read_b32 v19, a177
	v_accvgpr_read_b32 v17, a161
	s_waitcnt vmcnt(14)
	s_nop 1
	v_accvgpr_read_b32 v0, a192
	v_accvgpr_read_b32 v1, a193
	v_accvgpr_read_b32 v2, a194
	v_accvgpr_read_b32 v3, a195
	v_accvgpr_read_b32 v78, a196
	v_accvgpr_read_b32 v79, a197
	v_accvgpr_read_b32 v80, a198
	v_accvgpr_read_b32 v81, a199
	v_pk_mul_f32 v[44:45], v[18:19], v[78:79]
	s_nop 0
	v_pk_fma_f32 v[44:45], v[16:17], v[0:1], v[44:45] neg_lo:[0,0,1] neg_hi:[0,0,1]
	v_pk_mul_f32 v[16:17], v[16:17], v[78:79]
	v_pk_mul_f32 v[68:69], v[50:51], v[44:45] op_sel_hi:[0,1]
	v_pk_fma_f32 v[0:1], v[18:19], v[0:1], v[16:17]
	s_nop 0
	v_pk_mul_f32 v[48:49], v[50:51], v[0:1] op_sel_hi:[0,1]
	v_pk_mul_f32 v[0:1], v[70:71], v[80:81]
	v_cvt_pk_bf16_f32 v16, v48, v49
	v_pk_fma_f32 v[0:1], v[108:109], v[2:3], v[0:1] neg_lo:[0,0,1] neg_hi:[0,0,1]
	s_nop 0
	v_pk_mul_f32 v[62:63], v[50:51], v[0:1] op_sel_hi:[0,1]
	v_pk_mul_f32 v[0:1], v[108:109], v[80:81]
	s_nop 0
	v_pk_fma_f32 v[0:1], v[70:71], v[2:3], v[0:1]
	v_cvt_pk_bf16_f32 v2, v68, v69
	v_pk_mul_f32 v[44:45], v[50:51], v[0:1] op_sel_hi:[0,1]
	v_cvt_pk_bf16_f32 v3, v62, v63
	v_cvt_pk_bf16_f32 v17, v44, v45
	v_mad_u32_u24 v0, v60, s25, v51
	ds_write2_b64 v0, v[2:3], v[16:17] offset1:32
	s_waitcnt vmcnt(12)
	s_nop 1
	v_accvgpr_read_b32 v78, a200
	v_accvgpr_read_b32 v79, a201
	v_accvgpr_read_b32 v80, a202
	v_accvgpr_read_b32 v81, a203
	v_accvgpr_read_b32 v226, a204
	v_accvgpr_read_b32 v227, a205
	v_accvgpr_read_b32 v228, a206
	v_accvgpr_read_b32 v229, a207
	v_pk_mul_f32 v[2:3], v[206:207], v[226:227]
	s_nop 0
	v_pk_fma_f32 v[2:3], v[120:121], v[78:79], v[2:3] neg_lo:[0,0,1] neg_hi:[0,0,1]
	s_nop 0
	v_pk_mul_f32 v[108:109], v[50:51], v[2:3] op_sel_hi:[0,1]
	v_pk_mul_f32 v[2:3], v[120:121], v[226:227]
	s_nop 0
	v_pk_fma_f32 v[2:3], v[206:207], v[78:79], v[2:3]
	s_nop 0
	v_pk_mul_f32 v[72:73], v[50:51], v[2:3] op_sel_hi:[0,1]
	v_pk_mul_f32 v[2:3], v[164:165], v[228:229]
	v_cvt_pk_bf16_f32 v16, v72, v73
	v_pk_fma_f32 v[2:3], v[134:135], v[80:81], v[2:3] neg_lo:[0,0,1] neg_hi:[0,0,1]
	s_nop 0
	v_pk_mul_f32 v[120:121], v[50:51], v[2:3] op_sel_hi:[0,1]
	v_pk_mul_f32 v[2:3], v[134:135], v[228:229]
	s_nop 0
	v_pk_fma_f32 v[2:3], v[164:165], v[80:81], v[2:3]
	s_nop 0
	v_pk_mul_f32 v[70:71], v[50:51], v[2:3] op_sel_hi:[0,1]
	v_cvt_pk_bf16_f32 v2, v108, v109
	v_cvt_pk_bf16_f32 v3, v120, v121
	v_cvt_pk_bf16_f32 v17, v70, v71
	ds_write2_b64 v0, v[2:3], v[16:17] offset0:2 offset1:34
	s_waitcnt vmcnt(10)
	s_nop 1
	v_accvgpr_read_b32 v78, a208
	v_accvgpr_read_b32 v79, a209
	v_accvgpr_read_b32 v80, a210
	v_accvgpr_read_b32 v81, a211
	v_accvgpr_read_b32 v226, a212
	v_accvgpr_read_b32 v227, a213
	v_accvgpr_read_b32 v228, a214
	v_accvgpr_read_b32 v229, a215
	v_pk_mul_f32 v[2:3], v[136:137], v[226:227]
	s_nop 0
	v_pk_fma_f32 v[2:3], v[112:113], v[78:79], v[2:3] neg_lo:[0,0,1] neg_hi:[0,0,1]
	s_nop 0
	v_pk_mul_f32 v[134:135], v[50:51], v[2:3] op_sel_hi:[0,1]
	v_pk_mul_f32 v[2:3], v[112:113], v[226:227]
	s_nop 0
	v_pk_fma_f32 v[2:3], v[136:137], v[78:79], v[2:3]
	s_nop 0
	v_pk_mul_f32 v[112:113], v[50:51], v[2:3] op_sel_hi:[0,1]
	v_pk_mul_f32 v[2:3], v[152:153], v[228:229]
	v_cvt_pk_bf16_f32 v16, v112, v113
	v_pk_fma_f32 v[2:3], v[110:111], v[80:81], v[2:3] neg_lo:[0,0,1] neg_hi:[0,0,1]
	s_nop 0
	v_pk_mul_f32 v[136:137], v[50:51], v[2:3] op_sel_hi:[0,1]
	v_pk_mul_f32 v[2:3], v[110:111], v[228:229]
	s_nop 0
	v_pk_fma_f32 v[2:3], v[152:153], v[80:81], v[2:3]
	s_nop 0
	v_pk_mul_f32 v[110:111], v[50:51], v[2:3] op_sel_hi:[0,1]
	v_cvt_pk_bf16_f32 v2, v134, v135
	v_cvt_pk_bf16_f32 v3, v136, v137
	v_cvt_pk_bf16_f32 v17, v110, v111
	ds_write2_b64 v0, v[2:3], v[16:17] offset0:4 offset1:36
	s_waitcnt vmcnt(8)
	s_nop 1
	v_accvgpr_read_b32 v78, a216
	v_accvgpr_read_b32 v79, a217
	v_accvgpr_read_b32 v80, a218
	v_accvgpr_read_b32 v81, a219
	v_accvgpr_read_b32 v226, a220
	v_accvgpr_read_b32 v227, a221
	v_accvgpr_read_b32 v228, a222
	v_accvgpr_read_b32 v229, a223
	v_pk_mul_f32 v[2:3], v[154:155], v[226:227]
	s_nop 0
	v_pk_fma_f32 v[2:3], v[132:133], v[78:79], v[2:3] neg_lo:[0,0,1] neg_hi:[0,0,1]
	s_nop 0
	v_pk_mul_f32 v[152:153], v[50:51], v[2:3] op_sel_hi:[0,1]
	v_pk_mul_f32 v[2:3], v[132:133], v[226:227]
	s_nop 0
	v_pk_fma_f32 v[2:3], v[154:155], v[78:79], v[2:3]
	s_nop 0
	v_pk_mul_f32 v[132:133], v[50:51], v[2:3] op_sel_hi:[0,1]
	v_pk_mul_f32 v[2:3], v[146:147], v[228:229]
	v_cvt_pk_bf16_f32 v16, v132, v133
	v_pk_fma_f32 v[2:3], v[130:131], v[80:81], v[2:3] neg_lo:[0,0,1] neg_hi:[0,0,1]
	s_nop 0
	v_pk_mul_f32 v[154:155], v[50:51], v[2:3] op_sel_hi:[0,1]
	v_pk_mul_f32 v[2:3], v[130:131], v[228:229]
	s_nop 0
	v_pk_fma_f32 v[2:3], v[146:147], v[80:81], v[2:3]
	s_nop 0
	v_pk_mul_f32 v[130:131], v[50:51], v[2:3] op_sel_hi:[0,1]
	v_cvt_pk_bf16_f32 v2, v152, v153
	v_cvt_pk_bf16_f32 v3, v154, v155
	v_cvt_pk_bf16_f32 v17, v130, v131
	ds_write2_b64 v0, v[2:3], v[16:17] offset0:6 offset1:38
	v_accvgpr_read_b32 v16, a144
	v_accvgpr_read_b32 v2, a128
	v_accvgpr_read_b32 v17, a145
	v_accvgpr_read_b32 v3, a129
	s_waitcnt vmcnt(6)
	s_nop 1
	v_accvgpr_read_b32 v78, a224
	v_accvgpr_read_b32 v79, a225
	v_accvgpr_read_b32 v80, a226
	v_accvgpr_read_b32 v81, a227
	v_accvgpr_read_b32 v226, a228
	v_accvgpr_read_b32 v227, a229
	v_accvgpr_read_b32 v228, a230
	v_accvgpr_read_b32 v229, a231
	v_pk_mul_f32 v[18:19], v[16:17], v[226:227]
	s_nop 0
	v_pk_fma_f32 v[18:19], v[2:3], v[78:79], v[18:19] neg_lo:[0,0,1] neg_hi:[0,0,1]
	v_pk_mul_f32 v[2:3], v[2:3], v[226:227]
	v_pk_mul_f32 v[164:165], v[50:51], v[18:19] op_sel_hi:[0,1]
	v_pk_fma_f32 v[2:3], v[16:17], v[78:79], v[2:3]
	s_nop 0
	v_pk_mul_f32 v[146:147], v[50:51], v[2:3] op_sel_hi:[0,1]
	v_pk_mul_f32 v[2:3], v[180:181], v[228:229]
	v_cvt_pk_bf16_f32 v16, v146, v147
	v_pk_fma_f32 v[2:3], v[144:145], v[80:81], v[2:3] neg_lo:[0,0,1] neg_hi:[0,0,1]
	s_nop 0
	v_pk_mul_f32 v[168:169], v[50:51], v[2:3] op_sel_hi:[0,1]
	v_pk_mul_f32 v[2:3], v[144:145], v[228:229]
	s_nop 0
	v_pk_fma_f32 v[2:3], v[180:181], v[80:81], v[2:3]
	s_nop 0
	v_pk_mul_f32 v[144:145], v[50:51], v[2:3] op_sel_hi:[0,1]
	v_cvt_pk_bf16_f32 v2, v164, v165
	v_cvt_pk_bf16_f32 v3, v168, v169
	v_cvt_pk_bf16_f32 v17, v144, v145
	ds_write2_b64 v0, v[2:3], v[16:17] offset0:8 offset1:40
	s_waitcnt vmcnt(4)
	s_nop 1
	v_accvgpr_read_b32 v78, a232
	v_accvgpr_read_b32 v79, a233
	v_accvgpr_read_b32 v80, a234
	v_accvgpr_read_b32 v81, a235
	v_accvgpr_read_b32 v226, a236
	v_accvgpr_read_b32 v227, a237
	v_accvgpr_read_b32 v228, a238
	v_accvgpr_read_b32 v229, a239
	v_pk_mul_f32 v[2:3], v[182:183], v[226:227]
	s_nop 0
	v_pk_fma_f32 v[2:3], v[158:159], v[78:79], v[2:3] neg_lo:[0,0,1] neg_hi:[0,0,1]
	s_nop 0
	v_pk_mul_f32 v[180:181], v[50:51], v[2:3] op_sel_hi:[0,1]
	v_pk_mul_f32 v[2:3], v[158:159], v[226:227]
	s_nop 0
	v_pk_fma_f32 v[2:3], v[182:183], v[78:79], v[2:3]
	s_nop 0
	v_pk_mul_f32 v[158:159], v[50:51], v[2:3] op_sel_hi:[0,1]
	v_pk_mul_f32 v[2:3], v[200:201], v[228:229]
	v_cvt_pk_bf16_f32 v16, v158, v159
	v_pk_fma_f32 v[2:3], v[156:157], v[80:81], v[2:3] neg_lo:[0,0,1] neg_hi:[0,0,1]
	s_nop 0
	v_pk_mul_f32 v[182:183], v[50:51], v[2:3] op_sel_hi:[0,1]
	v_pk_mul_f32 v[2:3], v[156:157], v[228:229]
	s_nop 0
	v_pk_fma_f32 v[2:3], v[200:201], v[80:81], v[2:3]
	s_nop 0
	v_pk_mul_f32 v[156:157], v[50:51], v[2:3] op_sel_hi:[0,1]
	v_cvt_pk_bf16_f32 v2, v180, v181
	v_cvt_pk_bf16_f32 v3, v182, v183
	v_cvt_pk_bf16_f32 v17, v156, v157
	ds_write2_b64 v0, v[2:3], v[16:17] offset0:10 offset1:42
	s_waitcnt vmcnt(2)
	s_nop 1
	v_accvgpr_read_b32 v78, a240
	v_accvgpr_read_b32 v79, a241
	v_accvgpr_read_b32 v80, a242
	v_accvgpr_read_b32 v81, a243
	v_accvgpr_read_b32 v226, a244
	v_accvgpr_read_b32 v227, a245
	v_accvgpr_read_b32 v228, a246
	v_accvgpr_read_b32 v229, a247
	v_pk_mul_f32 v[2:3], v[198:199], v[226:227]
	s_nop 0
	v_pk_fma_f32 v[2:3], v[178:179], v[78:79], v[2:3] neg_lo:[0,0,1] neg_hi:[0,0,1]
	s_nop 0
	v_pk_mul_f32 v[206:207], v[50:51], v[2:3] op_sel_hi:[0,1]
	v_pk_mul_f32 v[2:3], v[178:179], v[226:227]
	s_nop 0
	v_pk_fma_f32 v[2:3], v[198:199], v[78:79], v[2:3]
	s_nop 0
	v_pk_mul_f32 v[178:179], v[50:51], v[2:3] op_sel_hi:[0,1]
	v_pk_mul_f32 v[2:3], v[4:5], v[228:229]
	s_nop 0
	v_pk_fma_f32 v[2:3], v[176:177], v[80:81], v[2:3] neg_lo:[0,0,1] neg_hi:[0,0,1]
	s_nop 0
	v_pk_mul_f32 v[210:211], v[50:51], v[2:3] op_sel_hi:[0,1]
	v_pk_mul_f32 v[2:3], v[176:177], v[228:229]
	s_nop 0
	v_pk_fma_f32 v[2:3], v[4:5], v[80:81], v[2:3]
	v_cvt_pk_bf16_f32 v4, v178, v179
	v_pk_mul_f32 v[176:177], v[50:51], v[2:3] op_sel_hi:[0,1]
	v_cvt_pk_bf16_f32 v2, v206, v207
	v_cvt_pk_bf16_f32 v3, v210, v211
	v_cvt_pk_bf16_f32 v5, v176, v177
	ds_write2_b64 v0, v[2:3], v[4:5] offset0:12 offset1:44
	s_nop 0
	s_waitcnt vmcnt(0)
	s_nop 1
	v_accvgpr_read_b32 v2, a248
	v_accvgpr_read_b32 v3, a249
	v_accvgpr_read_b32 v4, a250
	v_accvgpr_read_b32 v5, a251
	v_accvgpr_read_b32 v76, a252
	v_accvgpr_read_b32 v77, a253
	v_accvgpr_read_b32 v78, a254
	v_accvgpr_read_b32 v79, a255
	v_pk_mul_f32 v[6:7], v[196:197], v[76:77]
	s_nop 0
	v_pk_fma_f32 v[6:7], v[194:195], v[2:3], v[6:7] neg_lo:[0,0,1] neg_hi:[0,0,1]
	s_nop 0
	v_pk_mul_f32 v[226:227], v[50:51], v[6:7] op_sel_hi:[0,1]
	v_pk_mul_f32 v[6:7], v[194:195], v[76:77]
	s_nop 0
	v_pk_fma_f32 v[2:3], v[196:197], v[2:3], v[6:7]
	s_nop 0
	v_pk_mul_f32 v[196:197], v[50:51], v[2:3] op_sel_hi:[0,1]
	v_pk_mul_f32 v[2:3], v[12:13], v[78:79]
	s_nop 0
	v_pk_fma_f32 v[2:3], v[174:175], v[4:5], v[2:3] neg_lo:[0,0,1] neg_hi:[0,0,1]
	s_nop 0
	v_pk_mul_f32 v[228:229], v[50:51], v[2:3] op_sel_hi:[0,1]
	v_pk_mul_f32 v[2:3], v[174:175], v[78:79]
	s_nop 0
	v_pk_fma_f32 v[2:3], v[12:13], v[4:5], v[2:3]
	v_cvt_pk_bf16_f32 v4, v196, v197
	v_pk_mul_f32 v[198:199], v[50:51], v[2:3] op_sel_hi:[0,1]
	v_cvt_pk_bf16_f32 v2, v226, v227
	v_cvt_pk_bf16_f32 v3, v228, v229
	v_cvt_pk_bf16_f32 v5, v198, v199
	ds_write2_b64 v0, v[2:3], v[4:5] offset0:14 offset1:46
	v_or_b32_e32 v60, 64, v74
	v_or_b32_e32 v0, s66, v60
	v_lshlrev_b32_e32 v94, 9, v0
	v_lshl_add_u64 v[6:7], v[184:185], 0, v[94:95]
	v_lshl_add_u64 v[4:5], v[186:187], 0, v[94:95]
	global_load_dwordx4 a[192:195], v[6:7], off
	global_load_dwordx4 a[196:199], v[4:5], off
	global_load_dwordx4 a[200:203], v[6:7], off offset:32
	global_load_dwordx4 a[204:207], v[4:5], off offset:32
	global_load_dwordx4 a[208:211], v[6:7], off offset:64
	global_load_dwordx4 a[212:215], v[4:5], off offset:64
	global_load_dwordx4 a[216:219], v[6:7], off offset:96
	global_load_dwordx4 a[220:223], v[4:5], off offset:96
	global_load_dwordx4 a[224:227], v[6:7], off offset:128
	global_load_dwordx4 a[228:231], v[4:5], off offset:128
	global_load_dwordx4 a[232:235], v[6:7], off offset:160
	global_load_dwordx4 a[236:239], v[4:5], off offset:160
	global_load_dwordx4 a[240:243], v[6:7], off offset:192
	global_load_dwordx4 a[244:247], v[4:5], off offset:192
	global_load_dwordx4 a[248:251], v[6:7], off offset:224
	global_load_dwordx4 a[252:255], v[4:5], off offset:224
	v_accvgpr_read_b32 v16, a112
	v_accvgpr_read_b32 v12, a96
	v_accvgpr_read_b32 v17, a113
	v_accvgpr_read_b32 v13, a97
	s_waitcnt vmcnt(14)
	s_nop 1
	v_accvgpr_read_b32 v0, a192
	v_accvgpr_read_b32 v1, a193
	v_accvgpr_read_b32 v2, a194
	v_accvgpr_read_b32 v3, a195
	v_accvgpr_read_b32 v76, a196
	v_accvgpr_read_b32 v77, a197
	v_accvgpr_read_b32 v78, a198
	v_accvgpr_read_b32 v79, a199
	v_pk_mul_f32 v[18:19], v[16:17], v[76:77]
	s_nop 0
	v_pk_fma_f32 v[18:19], v[12:13], v[0:1], v[18:19] neg_lo:[0,0,1] neg_hi:[0,0,1]
	v_pk_mul_f32 v[12:13], v[12:13], v[76:77]
	v_pk_mul_f32 v[200:201], v[50:51], v[18:19] op_sel_hi:[0,1]
	v_pk_fma_f32 v[0:1], v[16:17], v[0:1], v[12:13]
	v_mad_u32_u24 v12, v60, s25, v51
	v_pk_mul_f32 v[174:175], v[50:51], v[0:1] op_sel_hi:[0,1]
	v_pk_mul_f32 v[0:1], v[216:217], v[78:79]
	s_nop 0
	v_pk_fma_f32 v[0:1], v[172:173], v[2:3], v[0:1] neg_lo:[0,0,1] neg_hi:[0,0,1]
	s_nop 0
	v_pk_mul_f32 v[194:195], v[50:51], v[0:1] op_sel_hi:[0,1]
	v_pk_mul_f32 v[0:1], v[172:173], v[78:79]
	s_nop 0
	v_pk_fma_f32 v[0:1], v[216:217], v[2:3], v[0:1]
	v_cvt_pk_bf16_f32 v2, v174, v175
	v_pk_mul_f32 v[172:173], v[50:51], v[0:1] op_sel_hi:[0,1]
	v_cvt_pk_bf16_f32 v0, v200, v201
	v_cvt_pk_bf16_f32 v1, v194, v195
	v_cvt_pk_bf16_f32 v3, v172, v173
	ds_write2_b64 v12, v[0:1], v[2:3] offset1:32
	s_waitcnt vmcnt(12)
	s_nop 1
	v_accvgpr_read_b32 v0, a200
	v_accvgpr_read_b32 v1, a201
	v_accvgpr_read_b32 v2, a202
	v_accvgpr_read_b32 v3, a203
	v_accvgpr_read_b32 v76, a204
	v_accvgpr_read_b32 v77, a205
	v_accvgpr_read_b32 v78, a206
	v_accvgpr_read_b32 v79, a207
	v_pk_mul_f32 v[16:17], v[232:233], v[76:77]
	s_nop 0
	v_pk_fma_f32 v[16:17], v[204:205], v[0:1], v[16:17] neg_lo:[0,0,1] neg_hi:[0,0,1]
	s_nop 0
	v_pk_mul_f32 v[216:217], v[50:51], v[16:17] op_sel_hi:[0,1]
	v_pk_mul_f32 v[16:17], v[204:205], v[76:77]
	s_nop 0
	v_pk_fma_f32 v[0:1], v[232:233], v[0:1], v[16:17]
	s_nop 0
	v_pk_mul_f32 v[204:205], v[50:51], v[0:1] op_sel_hi:[0,1]
	v_pk_mul_f32 v[0:1], v[224:225], v[78:79]
	s_nop 0
	v_pk_fma_f32 v[0:1], v[202:203], v[2:3], v[0:1] neg_lo:[0,0,1] neg_hi:[0,0,1]
	s_nop 0
	v_pk_mul_f32 v[232:233], v[50:51], v[0:1] op_sel_hi:[0,1]
	v_pk_mul_f32 v[0:1], v[202:203], v[78:79]
	s_nop 0
	v_pk_fma_f32 v[0:1], v[224:225], v[2:3], v[0:1]
	v_cvt_pk_bf16_f32 v2, v204, v205
	v_pk_mul_f32 v[202:203], v[50:51], v[0:1] op_sel_hi:[0,1]
	v_cvt_pk_bf16_f32 v0, v216, v217
	v_cvt_pk_bf16_f32 v1, v232, v233
	v_cvt_pk_bf16_f32 v3, v202, v203
	ds_write2_b64 v12, v[0:1], v[2:3] offset0:2 offset1:34
	s_waitcnt vmcnt(10)
	s_nop 1
	v_accvgpr_read_b32 v0, a208
	v_accvgpr_read_b32 v1, a209
	v_accvgpr_read_b32 v2, a210
	v_accvgpr_read_b32 v3, a211
	v_accvgpr_read_b32 v76, a212
	v_accvgpr_read_b32 v77, a213
	v_accvgpr_read_b32 v78, a214
	v_accvgpr_read_b32 v79, a215
	v_pk_mul_f32 v[16:17], v[236:237], v[76:77]
	s_nop 0
	v_pk_fma_f32 v[16:17], v[220:221], v[0:1], v[16:17] neg_lo:[0,0,1] neg_hi:[0,0,1]
	s_nop 0
	v_pk_mul_f32 v[234:235], v[50:51], v[16:17] op_sel_hi:[0,1]
	v_pk_mul_f32 v[16:17], v[220:221], v[76:77]
	s_nop 0
	v_pk_fma_f32 v[0:1], v[236:237], v[0:1], v[16:17]
	s_nop 0
	v_pk_mul_f32 v[220:221], v[50:51], v[0:1] op_sel_hi:[0,1]
	v_pk_mul_f32 v[0:1], v[246:247], v[78:79]
	s_nop 0
	v_pk_fma_f32 v[0:1], v[218:219], v[2:3], v[0:1] neg_lo:[0,0,1] neg_hi:[0,0,1]
	s_nop 0
	v_pk_mul_f32 v[236:237], v[50:51], v[0:1] op_sel_hi:[0,1]
	v_pk_mul_f32 v[0:1], v[218:219], v[78:79]
	s_nop 0
	v_pk_fma_f32 v[0:1], v[246:247], v[2:3], v[0:1]
	v_cvt_pk_bf16_f32 v2, v220, v221
	v_pk_mul_f32 v[218:219], v[50:51], v[0:1] op_sel_hi:[0,1]
	v_cvt_pk_bf16_f32 v0, v234, v235
	v_cvt_pk_bf16_f32 v1, v236, v237
	v_cvt_pk_bf16_f32 v3, v218, v219
	ds_write2_b64 v12, v[0:1], v[2:3] offset0:4 offset1:36
	s_waitcnt vmcnt(8)
	s_nop 1
	v_accvgpr_read_b32 v0, a216
	v_accvgpr_read_b32 v1, a217
	v_accvgpr_read_b32 v2, a218
	v_accvgpr_read_b32 v3, a219
	v_accvgpr_read_b32 v76, a220
	v_accvgpr_read_b32 v77, a221
	v_accvgpr_read_b32 v78, a222
	v_accvgpr_read_b32 v79, a223
	v_pk_mul_f32 v[16:17], v[244:245], v[76:77]
	s_nop 0
	v_pk_fma_f32 v[16:17], v[212:213], v[0:1], v[16:17] neg_lo:[0,0,1] neg_hi:[0,0,1]
	s_nop 0
	v_pk_mul_f32 v[246:247], v[50:51], v[16:17] op_sel_hi:[0,1]
	v_pk_mul_f32 v[16:17], v[212:213], v[76:77]
	s_nop 0
	v_pk_fma_f32 v[0:1], v[244:245], v[0:1], v[16:17]
	s_nop 0
	v_pk_mul_f32 v[212:213], v[50:51], v[0:1] op_sel_hi:[0,1]
	v_pk_mul_f32 v[0:1], v[242:243], v[78:79]
	v_accvgpr_read_b32 v18, a80
	v_pk_fma_f32 v[0:1], v[208:209], v[2:3], v[0:1] neg_lo:[0,0,1] neg_hi:[0,0,1]
	v_accvgpr_read_b32 v16, a64
	v_pk_mul_f32 v[244:245], v[50:51], v[0:1] op_sel_hi:[0,1]
	v_pk_mul_f32 v[0:1], v[208:209], v[78:79]
	v_accvgpr_read_b32 v19, a81
	v_pk_fma_f32 v[0:1], v[242:243], v[2:3], v[0:1]
	v_cvt_pk_bf16_f32 v2, v212, v213
	v_pk_mul_f32 v[208:209], v[50:51], v[0:1] op_sel_hi:[0,1]
	v_cvt_pk_bf16_f32 v0, v246, v247
	v_cvt_pk_bf16_f32 v1, v244, v245
	v_cvt_pk_bf16_f32 v3, v208, v209
	ds_write2_b64 v12, v[0:1], v[2:3] offset0:6 offset1:38
	v_accvgpr_read_b32 v17, a65
	s_waitcnt vmcnt(6)
	s_nop 1
	v_accvgpr_read_b32 v0, a224
	v_accvgpr_read_b32 v1, a225
	v_accvgpr_read_b32 v2, a226
	v_accvgpr_read_b32 v3, a227
	v_accvgpr_read_b32 v76, a228
	v_accvgpr_read_b32 v77, a229
	v_accvgpr_read_b32 v78, a230
	v_accvgpr_read_b32 v79, a231
	v_pk_mul_f32 v[60:61], v[18:19], v[76:77]
	s_nop 0
	v_pk_fma_f32 v[60:61], v[16:17], v[0:1], v[60:61] neg_lo:[0,0,1] neg_hi:[0,0,1]
	v_pk_mul_f32 v[16:17], v[16:17], v[76:77]
	v_pk_mul_f32 v[252:253], v[50:51], v[60:61] op_sel_hi:[0,1]
	v_pk_fma_f32 v[0:1], v[18:19], v[0:1], v[16:17]
	s_nop 0
	v_pk_mul_f32 v[242:243], v[50:51], v[0:1] op_sel_hi:[0,1]
	v_pk_mul_f32 v[0:1], v[10:11], v[78:79]
	v_pk_mul_f32 v[16:17], v[214:215], v[78:79]
	v_pk_fma_f32 v[0:1], v[214:215], v[2:3], v[0:1] neg_lo:[0,0,1] neg_hi:[0,0,1]
	v_pk_fma_f32 v[2:3], v[10:11], v[2:3], v[16:17]
	v_pk_mul_f32 v[0:1], v[50:51], v[0:1] op_sel_hi:[0,1]
	v_pk_mul_f32 v[214:215], v[50:51], v[2:3] op_sel_hi:[0,1]
	v_cvt_pk_bf16_f32 v2, v252, v253
	v_cvt_pk_bf16_f32 v3, v0, v1
	v_cvt_pk_bf16_f32 v10, v242, v243
	v_cvt_pk_bf16_f32 v11, v214, v215
	ds_write2_b64 v12, v[2:3], v[10:11] offset0:8 offset1:40
	s_waitcnt vmcnt(4)
	s_nop 1
	v_accvgpr_read_b32 v76, a232
	v_accvgpr_read_b32 v77, a233
	v_accvgpr_read_b32 v78, a234
	v_accvgpr_read_b32 v79, a235
	v_accvgpr_read_b32 v16, a236
	v_accvgpr_read_b32 v17, a237
	v_accvgpr_read_b32 v18, a238
	v_accvgpr_read_b32 v19, a239
	v_pk_mul_f32 v[2:3], v[250:251], v[16:17]
	v_pk_mul_f32 v[10:11], v[190:191], v[16:17]
	v_pk_fma_f32 v[2:3], v[190:191], v[76:77], v[2:3] neg_lo:[0,0,1] neg_hi:[0,0,1]
	v_pk_fma_f32 v[10:11], v[250:251], v[76:77], v[10:11]
	v_pk_mul_f32 v[2:3], v[50:51], v[2:3] op_sel_hi:[0,1]
	v_pk_mul_f32 v[190:191], v[50:51], v[10:11] op_sel_hi:[0,1]
	v_pk_mul_f32 v[10:11], v[248:249], v[18:19]
	v_cvt_pk_bf16_f32 v16, v190, v191
	v_pk_fma_f32 v[10:11], v[188:189], v[78:79], v[10:11] neg_lo:[0,0,1] neg_hi:[0,0,1]
	s_nop 0
	v_pk_mul_f32 v[250:251], v[50:51], v[10:11] op_sel_hi:[0,1]
	v_pk_mul_f32 v[10:11], v[188:189], v[18:19]
	s_nop 0
	v_pk_fma_f32 v[10:11], v[248:249], v[78:79], v[10:11]
	s_nop 0
	v_pk_mul_f32 v[188:189], v[50:51], v[10:11] op_sel_hi:[0,1]
	v_cvt_pk_bf16_f32 v10, v2, v3
	v_cvt_pk_bf16_f32 v11, v250, v251
	v_cvt_pk_bf16_f32 v17, v188, v189
	ds_write2_b64 v12, v[10:11], v[16:17] offset0:10 offset1:42
	s_waitcnt vmcnt(2)
	s_nop 1
	v_accvgpr_read_b32 v16, a240
	v_accvgpr_read_b32 v17, a241
	v_accvgpr_read_b32 v18, a242
	v_accvgpr_read_b32 v19, a243
	v_accvgpr_read_b32 v76, a244
	v_accvgpr_read_b32 v77, a245
	v_accvgpr_read_b32 v78, a246
	v_accvgpr_read_b32 v79, a247
	v_pk_mul_f32 v[10:11], v[240:241], v[76:77]
	s_nop 0
	v_pk_fma_f32 v[10:11], v[170:171], v[16:17], v[10:11] neg_lo:[0,0,1] neg_hi:[0,0,1]
	s_nop 0
	v_pk_mul_f32 v[248:249], v[50:51], v[10:11] op_sel_hi:[0,1]
	v_pk_mul_f32 v[10:11], v[170:171], v[76:77]
	s_nop 0
	v_pk_fma_f32 v[10:11], v[240:241], v[16:17], v[10:11]
	s_nop 0
	v_pk_mul_f32 v[170:171], v[50:51], v[10:11] op_sel_hi:[0,1]
	v_pk_mul_f32 v[10:11], v[238:239], v[78:79]
	v_cvt_pk_bf16_f32 v16, v170, v171
	v_pk_fma_f32 v[10:11], v[162:163], v[18:19], v[10:11] neg_lo:[0,0,1] neg_hi:[0,0,1]
	s_nop 0
	v_pk_mul_f32 v[240:241], v[50:51], v[10:11] op_sel_hi:[0,1]
	v_pk_mul_f32 v[10:11], v[162:163], v[78:79]
	s_nop 0
	v_pk_fma_f32 v[10:11], v[238:239], v[18:19], v[10:11]
	s_nop 0
	v_pk_mul_f32 v[162:163], v[50:51], v[10:11] op_sel_hi:[0,1]
	v_cvt_pk_bf16_f32 v10, v248, v249
	v_cvt_pk_bf16_f32 v11, v240, v241
	v_cvt_pk_bf16_f32 v17, v162, v163
	ds_write2_b64 v12, v[10:11], v[16:17] offset0:12 offset1:44
	s_nop 0
	s_waitcnt vmcnt(0)
	s_nop 1
	v_accvgpr_read_b32 v16, a248
	v_accvgpr_read_b32 v17, a249
	v_accvgpr_read_b32 v18, a250
	v_accvgpr_read_b32 v19, a251
	v_accvgpr_read_b32 v4, a252
	v_accvgpr_read_b32 v5, a253
	v_accvgpr_read_b32 v6, a254
	v_accvgpr_read_b32 v7, a255
	v_pk_mul_f32 v[10:11], v[230:231], v[4:5]
	v_pk_mul_f32 v[4:5], v[150:151], v[4:5]
	v_pk_fma_f32 v[10:11], v[150:151], v[16:17], v[10:11] neg_lo:[0,0,1] neg_hi:[0,0,1]
	v_pk_fma_f32 v[4:5], v[230:231], v[16:17], v[4:5]
	v_pk_mul_f32 v[238:239], v[50:51], v[10:11] op_sel_hi:[0,1]
	v_pk_mul_f32 v[224:225], v[50:51], v[4:5] op_sel_hi:[0,1]
	v_pk_mul_f32 v[4:5], v[222:223], v[6:7]
	s_nop 0
	v_pk_fma_f32 v[4:5], v[148:149], v[18:19], v[4:5] neg_lo:[0,0,1] neg_hi:[0,0,1]
	s_nop 0
	v_pk_mul_f32 v[230:231], v[50:51], v[4:5] op_sel_hi:[0,1]
	v_pk_mul_f32 v[4:5], v[148:149], v[6:7]
	v_cvt_pk_bf16_f32 v6, v224, v225
	v_pk_fma_f32 v[4:5], v[222:223], v[18:19], v[4:5]
	s_nop 0
	v_pk_mul_f32 v[222:223], v[50:51], v[4:5] op_sel_hi:[0,1]
	v_cvt_pk_bf16_f32 v4, v238, v239
	v_cvt_pk_bf16_f32 v5, v230, v231
	v_cvt_pk_bf16_f32 v7, v222, v223
	ds_write2_b64 v12, v[4:5], v[6:7] offset0:14 offset1:46
	v_or_b32_e32 v78, 0x60, v74
	v_or_b32_e32 v4, s66, v78
	v_lshlrev_b32_e32 v94, 9, v4
	v_lshl_add_u64 v[76:77], v[184:185], 0, v[94:95]
	v_lshl_add_u64 v[6:7], v[186:187], 0, v[94:95]
	global_load_dwordx4 a[192:195], v[76:77], off
	global_load_dwordx4 a[196:199], v[6:7], off
	global_load_dwordx4 a[200:203], v[76:77], off offset:32
	global_load_dwordx4 a[204:207], v[6:7], off offset:32
	global_load_dwordx4 a[208:211], v[76:77], off offset:64
	global_load_dwordx4 a[212:215], v[6:7], off offset:64
	global_load_dwordx4 a[216:219], v[76:77], off offset:96
	global_load_dwordx4 a[220:223], v[6:7], off offset:96
	global_load_dwordx4 a[224:227], v[76:77], off offset:128
	global_load_dwordx4 a[228:231], v[6:7], off offset:128
	global_load_dwordx4 a[232:235], v[76:77], off offset:160
	global_load_dwordx4 a[236:239], v[6:7], off offset:160
	global_load_dwordx4 a[240:243], v[76:77], off offset:192
	global_load_dwordx4 a[244:247], v[6:7], off offset:192
	global_load_dwordx4 a[248:251], v[76:77], off offset:224
	global_load_dwordx4 a[252:255], v[6:7], off offset:224
	v_accvgpr_read_b32 v61, a49
	v_accvgpr_read_b32 v4, a32
	v_accvgpr_read_b32 v60, a48
	v_accvgpr_read_b32 v5, a33
	s_waitcnt vmcnt(14)
	s_nop 1
	v_accvgpr_read_b32 v10, a192
	v_accvgpr_read_b32 v11, a193
	v_accvgpr_read_b32 v12, a194
	v_accvgpr_read_b32 v13, a195
	v_accvgpr_read_b32 v16, a196
	v_accvgpr_read_b32 v17, a197
	v_accvgpr_read_b32 v18, a198
	v_accvgpr_read_b32 v19, a199
	v_pk_mul_f32 v[74:75], v[60:61], v[16:17]
	s_nop 0
	v_pk_fma_f32 v[74:75], v[4:5], v[10:11], v[74:75] neg_lo:[0,0,1] neg_hi:[0,0,1]
	v_pk_mul_f32 v[4:5], v[4:5], v[16:17]
	v_pk_mul_f32 v[184:185], v[50:51], v[74:75] op_sel_hi:[0,1]
	v_pk_fma_f32 v[4:5], v[60:61], v[10:11], v[4:5]
	v_mad_u32_u24 v10, v78, s25, v51
	v_pk_mul_f32 v[148:149], v[50:51], v[4:5] op_sel_hi:[0,1]
	v_pk_mul_f32 v[4:5], v[192:193], v[18:19]
	s_nop 0
	v_pk_fma_f32 v[4:5], v[128:129], v[12:13], v[4:5] neg_lo:[0,0,1] neg_hi:[0,0,1]
	s_nop 0
	v_pk_mul_f32 v[150:151], v[50:51], v[4:5] op_sel_hi:[0,1]
	v_pk_mul_f32 v[4:5], v[128:129], v[18:19]
	s_nop 0
	v_pk_fma_f32 v[4:5], v[192:193], v[12:13], v[4:5]
	v_cvt_pk_bf16_f32 v12, v148, v149
	v_pk_mul_f32 v[128:129], v[50:51], v[4:5] op_sel_hi:[0,1]
	v_cvt_pk_bf16_f32 v4, v184, v185
	v_cvt_pk_bf16_f32 v5, v150, v151
	v_cvt_pk_bf16_f32 v13, v128, v129
	ds_write2_b64 v10, v[4:5], v[12:13] offset1:32
	s_waitcnt vmcnt(12)
	s_nop 1
	v_accvgpr_read_b32 v16, a200
	v_accvgpr_read_b32 v17, a201
	v_accvgpr_read_b32 v18, a202
	v_accvgpr_read_b32 v19, a203
	v_accvgpr_read_b32 v78, a204
	v_accvgpr_read_b32 v79, a205
	v_accvgpr_read_b32 v80, a206
	v_accvgpr_read_b32 v81, a207
	v_pk_mul_f32 v[4:5], v[166:167], v[78:79]
	s_nop 0
	v_pk_fma_f32 v[4:5], v[106:107], v[16:17], v[4:5] neg_lo:[0,0,1] neg_hi:[0,0,1]
	s_nop 0
	v_pk_mul_f32 v[186:187], v[50:51], v[4:5] op_sel_hi:[0,1]
	v_pk_mul_f32 v[4:5], v[106:107], v[78:79]
	s_nop 0
	v_pk_fma_f32 v[4:5], v[166:167], v[16:17], v[4:5]
	s_nop 0
	v_pk_mul_f32 v[106:107], v[50:51], v[4:5] op_sel_hi:[0,1]
	v_pk_mul_f32 v[4:5], v[160:161], v[80:81]
	v_cvt_pk_bf16_f32 v12, v106, v107
	v_pk_fma_f32 v[4:5], v[98:99], v[18:19], v[4:5] neg_lo:[0,0,1] neg_hi:[0,0,1]
	s_nop 0
	v_pk_mul_f32 v[166:167], v[50:51], v[4:5] op_sel_hi:[0,1]
	v_pk_mul_f32 v[4:5], v[98:99], v[80:81]
	s_nop 0
	v_pk_fma_f32 v[4:5], v[160:161], v[18:19], v[4:5]
	s_nop 0
	v_pk_mul_f32 v[98:99], v[50:51], v[4:5] op_sel_hi:[0,1]
	v_cvt_pk_bf16_f32 v4, v186, v187
	v_cvt_pk_bf16_f32 v5, v166, v167
	v_cvt_pk_bf16_f32 v13, v98, v99
	ds_write2_b64 v10, v[4:5], v[12:13] offset0:2 offset1:34
	s_waitcnt vmcnt(10)
	s_nop 1
	v_accvgpr_read_b32 v16, a208
	v_accvgpr_read_b32 v17, a209
	v_accvgpr_read_b32 v18, a210
	v_accvgpr_read_b32 v19, a211
	v_accvgpr_read_b32 v78, a212
	v_accvgpr_read_b32 v79, a213
	v_accvgpr_read_b32 v80, a214
	v_accvgpr_read_b32 v81, a215
	v_pk_mul_f32 v[4:5], v[142:143], v[78:79]
	s_nop 0
	v_pk_fma_f32 v[4:5], v[96:97], v[16:17], v[4:5] neg_lo:[0,0,1] neg_hi:[0,0,1]
	s_nop 0
	v_pk_mul_f32 v[160:161], v[50:51], v[4:5] op_sel_hi:[0,1]
	v_pk_mul_f32 v[4:5], v[96:97], v[78:79]
	s_nop 0
	v_pk_fma_f32 v[4:5], v[142:143], v[16:17], v[4:5]
	s_nop 0
	v_pk_mul_f32 v[96:97], v[50:51], v[4:5] op_sel_hi:[0,1]
	v_pk_mul_f32 v[4:5], v[140:141], v[80:81]
	v_cvt_pk_bf16_f32 v12, v96, v97
	v_pk_fma_f32 v[4:5], v[86:87], v[18:19], v[4:5] neg_lo:[0,0,1] neg_hi:[0,0,1]
	s_nop 0
	v_pk_mul_f32 v[142:143], v[50:51], v[4:5] op_sel_hi:[0,1]
	v_pk_mul_f32 v[4:5], v[86:87], v[80:81]
	s_nop 0
	v_pk_fma_f32 v[4:5], v[140:141], v[18:19], v[4:5]
	s_nop 0
	v_pk_mul_f32 v[20:21], v[50:51], v[4:5] op_sel_hi:[0,1]
	v_cvt_pk_bf16_f32 v4, v160, v161
	v_cvt_pk_bf16_f32 v5, v142, v143
	v_cvt_pk_bf16_f32 v13, v20, v21
	ds_write2_b64 v10, v[4:5], v[12:13] offset0:4 offset1:36
	s_waitcnt vmcnt(8)
	s_nop 1
	v_accvgpr_read_b32 v16, a216
	v_accvgpr_read_b32 v17, a217
	v_accvgpr_read_b32 v18, a218
	v_accvgpr_read_b32 v19, a219
	v_accvgpr_read_b32 v78, a220
	v_accvgpr_read_b32 v79, a221
	v_accvgpr_read_b32 v80, a222
	v_accvgpr_read_b32 v81, a223
	v_pk_mul_f32 v[4:5], v[126:127], v[78:79]
	s_nop 0
	v_pk_fma_f32 v[4:5], v[90:91], v[16:17], v[4:5] neg_lo:[0,0,1] neg_hi:[0,0,1]
	s_nop 0
	v_pk_mul_f32 v[140:141], v[50:51], v[4:5] op_sel_hi:[0,1]
	v_pk_mul_f32 v[4:5], v[90:91], v[78:79]
	s_nop 0
	v_pk_fma_f32 v[4:5], v[126:127], v[16:17], v[4:5]
	s_nop 0
	v_pk_mul_f32 v[90:91], v[50:51], v[4:5] op_sel_hi:[0,1]
	v_pk_mul_f32 v[4:5], v[124:125], v[80:81]
	v_cvt_pk_bf16_f32 v12, v90, v91
	v_pk_fma_f32 v[4:5], v[88:89], v[18:19], v[4:5] neg_lo:[0,0,1] neg_hi:[0,0,1]
	s_nop 0
	v_pk_mul_f32 v[126:127], v[50:51], v[4:5] op_sel_hi:[0,1]
	v_pk_mul_f32 v[4:5], v[88:89], v[80:81]
	s_nop 0
	v_pk_fma_f32 v[4:5], v[124:125], v[18:19], v[4:5]
	s_nop 0
	v_pk_mul_f32 v[88:89], v[50:51], v[4:5] op_sel_hi:[0,1]
	v_cvt_pk_bf16_f32 v4, v140, v141
	v_cvt_pk_bf16_f32 v5, v126, v127
	v_cvt_pk_bf16_f32 v13, v88, v89
	ds_write2_b64 v10, v[4:5], v[12:13] offset0:6 offset1:38
	v_accvgpr_read_b32 v12, a16
	v_accvgpr_read_b32 v5, a1
	v_accvgpr_read_b32 v13, a17
	v_accvgpr_read_b32 v4, a0
	s_waitcnt vmcnt(6)
	s_nop 1
	v_accvgpr_read_b32 v16, a224
	v_accvgpr_read_b32 v17, a225
	v_accvgpr_read_b32 v18, a226
	v_accvgpr_read_b32 v19, a227
	v_accvgpr_read_b32 v78, a228
	v_accvgpr_read_b32 v79, a229
	v_accvgpr_read_b32 v80, a230
	v_accvgpr_read_b32 v81, a231
	v_pk_mul_f32 v[60:61], v[12:13], v[78:79]
	s_nop 0
	v_pk_fma_f32 v[60:61], v[4:5], v[16:17], v[60:61] neg_lo:[0,0,1] neg_hi:[0,0,1]
	v_pk_mul_f32 v[4:5], v[4:5], v[78:79]
	v_pk_mul_f32 v[192:193], v[50:51], v[60:61] op_sel_hi:[0,1]
	v_pk_fma_f32 v[4:5], v[12:13], v[16:17], v[4:5]
	s_nop 0
	v_pk_mul_f32 v[124:125], v[50:51], v[4:5] op_sel_hi:[0,1]
	v_pk_mul_f32 v[4:5], v[138:139], v[80:81]
	v_pk_mul_f32 v[12:13], v[92:93], v[80:81]
	v_pk_fma_f32 v[4:5], v[92:93], v[18:19], v[4:5] neg_lo:[0,0,1] neg_hi:[0,0,1]
	v_pk_fma_f32 v[12:13], v[138:139], v[18:19], v[12:13]
	v_pk_mul_f32 v[4:5], v[50:51], v[4:5] op_sel_hi:[0,1]
	v_pk_mul_f32 v[92:93], v[50:51], v[12:13] op_sel_hi:[0,1]
	v_cvt_pk_bf16_f32 v12, v192, v193
	v_cvt_pk_bf16_f32 v13, v4, v5
	v_cvt_pk_bf16_f32 v16, v124, v125
	v_cvt_pk_bf16_f32 v17, v92, v93
	ds_write2_b64 v10, v[12:13], v[16:17] offset0:8 offset1:40
	s_waitcnt vmcnt(4)
	s_nop 1
	v_accvgpr_read_b32 v16, a232
	v_accvgpr_read_b32 v17, a233
	v_accvgpr_read_b32 v18, a234
	v_accvgpr_read_b32 v19, a235
	v_accvgpr_read_b32 v78, a236
	v_accvgpr_read_b32 v79, a237
	v_accvgpr_read_b32 v80, a238
	v_accvgpr_read_b32 v81, a239
	v_pk_mul_f32 v[12:13], v[122:123], v[78:79]
	s_nop 0
	v_pk_fma_f32 v[12:13], v[82:83], v[16:17], v[12:13] neg_lo:[0,0,1] neg_hi:[0,0,1]
	s_nop 0
	v_pk_mul_f32 v[138:139], v[50:51], v[12:13] op_sel_hi:[0,1]
	v_pk_mul_f32 v[12:13], v[82:83], v[78:79]
	s_nop 0
	v_pk_fma_f32 v[12:13], v[122:123], v[16:17], v[12:13]
	s_nop 0
	v_pk_mul_f32 v[86:87], v[50:51], v[12:13] op_sel_hi:[0,1]
	v_pk_mul_f32 v[12:13], v[116:117], v[80:81]
	v_cvt_pk_bf16_f32 v16, v86, v87
	v_pk_fma_f32 v[12:13], v[84:85], v[18:19], v[12:13] neg_lo:[0,0,1] neg_hi:[0,0,1]
	v_accvgpr_read_b32 v61, a39
	v_pk_mul_f32 v[122:123], v[50:51], v[12:13] op_sel_hi:[0,1]
	v_pk_mul_f32 v[12:13], v[84:85], v[80:81]
	v_accvgpr_read_b32 v60, a38
	v_pk_fma_f32 v[12:13], v[116:117], v[18:19], v[12:13]
	s_nop 0
	v_pk_mul_f32 v[84:85], v[50:51], v[12:13] op_sel_hi:[0,1]
	v_cvt_pk_bf16_f32 v12, v138, v139
	v_cvt_pk_bf16_f32 v13, v122, v123
	v_cvt_pk_bf16_f32 v17, v84, v85
	ds_write2_b64 v10, v[12:13], v[16:17] offset0:10 offset1:42
	s_waitcnt vmcnt(2)
	s_nop 1
	v_accvgpr_read_b32 v16, a240
	v_accvgpr_read_b32 v17, a241
	v_accvgpr_read_b32 v18, a242
	v_accvgpr_read_b32 v19, a243
	v_accvgpr_read_b32 v78, a244
	v_accvgpr_read_b32 v79, a245
	v_accvgpr_read_b32 v80, a246
	v_accvgpr_read_b32 v81, a247
	v_pk_mul_f32 v[12:13], v[102:103], v[78:79]
	s_nop 0
	v_pk_fma_f32 v[12:13], v[60:61], v[16:17], v[12:13] neg_lo:[0,0,1] neg_hi:[0,0,1]
	s_nop 0
	v_pk_mul_f32 v[116:117], v[50:51], v[12:13] op_sel_hi:[0,1]
	v_pk_mul_f32 v[12:13], v[60:61], v[78:79]
	s_nop 0
	v_pk_fma_f32 v[12:13], v[102:103], v[16:17], v[12:13]
	s_nop 0
	v_pk_mul_f32 v[82:83], v[50:51], v[12:13] op_sel_hi:[0,1]
	v_accvgpr_read_b32 v16, a36
	v_pk_mul_f32 v[12:13], v[8:9], v[80:81]
	v_accvgpr_read_b32 v17, a37
	v_pk_fma_f32 v[12:13], v[16:17], v[18:19], v[12:13] neg_lo:[0,0,1] neg_hi:[0,0,1]
	v_accvgpr_read_b32 v61, a13
	v_pk_mul_f32 v[102:103], v[50:51], v[12:13] op_sel_hi:[0,1]
	v_pk_mul_f32 v[12:13], v[16:17], v[80:81]
	v_accvgpr_read_b32 v60, a12
	v_pk_fma_f32 v[8:9], v[8:9], v[18:19], v[12:13]
	v_cvt_pk_bf16_f32 v12, v82, v83
	v_pk_mul_f32 v[74:75], v[50:51], v[8:9] op_sel_hi:[0,1]
	v_cvt_pk_bf16_f32 v8, v116, v117
	v_cvt_pk_bf16_f32 v9, v102, v103
	v_cvt_pk_bf16_f32 v13, v74, v75
	ds_write2_b64 v10, v[8:9], v[12:13] offset0:12 offset1:44
	s_nop 0
	s_waitcnt vmcnt(0)
	s_nop 1
	v_accvgpr_read_b32 v16, a248
	v_accvgpr_read_b32 v17, a249
	v_accvgpr_read_b32 v18, a250
	v_accvgpr_read_b32 v19, a251
	v_accvgpr_read_b32 v6, a252
	v_accvgpr_read_b32 v7, a253
	v_accvgpr_read_b32 v8, a254
	v_accvgpr_read_b32 v9, a255
	v_pk_mul_f32 v[12:13], v[56:57], v[6:7]
	v_pk_mul_f32 v[6:7], v[60:61], v[6:7]
	v_pk_fma_f32 v[12:13], v[60:61], v[16:17], v[12:13] neg_lo:[0,0,1] neg_hi:[0,0,1]
	v_pk_fma_f32 v[6:7], v[56:57], v[16:17], v[6:7]
	v_pk_mul_f32 v[80:81], v[50:51], v[12:13] op_sel_hi:[0,1]
	v_pk_mul_f32 v[56:57], v[50:51], v[6:7] op_sel_hi:[0,1]
	v_accvgpr_read_b32 v12, a14
	v_pk_mul_f32 v[6:7], v[46:47], v[8:9]
	v_accvgpr_read_b32 v13, a15
	v_pk_fma_f32 v[6:7], v[12:13], v[18:19], v[6:7] neg_lo:[0,0,1] neg_hi:[0,0,1]
	s_nop 0
	v_pk_mul_f32 v[78:79], v[50:51], v[6:7] op_sel_hi:[0,1]
	v_pk_mul_f32 v[6:7], v[12:13], v[8:9]
	v_cvt_pk_bf16_f32 v8, v56, v57
	v_pk_fma_f32 v[6:7], v[46:47], v[18:19], v[6:7]
	s_nop 0
	v_pk_mul_f32 v[46:47], v[50:51], v[6:7] op_sel_hi:[0,1]
	v_cvt_pk_bf16_f32 v6, v80, v81
	v_cvt_pk_bf16_f32 v7, v78, v79
	v_cvt_pk_bf16_f32 v9, v46, v47
	ds_write2_b64 v10, v[6:7], v[8:9] offset0:14 offset1:46
	s_and_b64 s[10:11], vcc, exec
	s_cselect_b32 s10, s36, 0x16100000
	s_add_u32 s12, s92, s10
	s_addc_u32 s13, s93, 0
	s_lshl_b64 s[10:11], s[40:41], 1
	s_add_u32 s12, s12, s10
	s_addc_u32 s11, s13, s11
	s_lshl_b32 s10, s4, 8
	s_lshl_b32 s13, s4, 9
	s_add_u32 s12, s12, s13
	s_addc_u32 s13, s11, 0
	s_mov_b32 s11, 0
	s_waitcnt lgkmcnt(0)
	s_barrier
	s_nop 0
	v_mbcnt_lo_u32_b32 v6, -1, s11
	v_mbcnt_hi_u32_b32 v6, -1, v6
	v_or_b32_e32 v8, s60, v6
	v_lshlrev_b32_e32 v6, 4, v6
	v_and_b32_e32 v94, 0x1f0, v6
	v_lshl_add_u64 v[6:7], s[12:13], 0, v[94:95]
